# forget-gate tail: gate-weight loads issued ahead of the row-chunk loads; counted vmcnt waits (weights drained first, rows as consumed) instead of one full drain
# baseline (speedup 1.0000x reference)
; #define LAS __attribute__((address_space(3)))
; __device__ __forceinline__ void fg_tail(const Args& a, int l, LAS unsigned char* lds, const int tid) {
;     ...
;     LAS f32x4* wl = (LAS f32x4*)lds;
;     {
;         const f32x4* wsrc = (const f32x4*)((const float*)(ws + WS_WFGT) + (size_t)l * 8192);
; #pragma unroll
;         for (int i = 0; i < 4; ++i) { const int idx = tid + 512 * i, j = idx >> 8, k4 = idx & 255, ln = k4 >> 2, q = k4 & 3; wl[(j * 4 + q) * 64 + ln] = wsrc[idx]; }
;     }
;     __syncthreads();
;     const bf16_t* H = (const bf16_t*)(ws + WS_H); const float* rowss = (const float*)(ws + WS_ROWSS) + (size_t)(2 * l) * MT * 4;
;     const float* mod = (const float*)(ws + WS_MOD) + (size_t)l * 8 * MODW; float* logf = (float*)(ws + WS_LOGF);
;     const float bfv = a.in[7][l * 8 + (lane >> 3)];
;     for (int chunk = blockIdx.x * 8 + wid; chunk * 8 < MT; chunk += gridDim.x * 8) {
;         const int rowc = chunk * 8, b = rowc >> 11;
;         f32x4 sh[4];
; #pragma unroll
;         for (int q = 0; q < 4; ++q) sh[q] = *(const f32x4*)(mod + (size_t)b * MODW + 16 * lane + 4 * q);
; #pragma unroll 1
;         for (int jb = 0; jb < 8; jb += 4) {
;             f32x4 rs4v[4]; u32x4 w0v[4], w1v[4];
; #pragma unroll
;             for (int j = 0; j < 4; ++j) { const int row = rowc + jb + j; rs4v[j] = *(const f32x4*)(rowss + (size_t)row * 4); w0v[j] = *(const u32x4*)(H + (size_t)row * DM + 16 * lane); w1v[j] = *(const u32x4*)(H + (size_t)row * DM + 16 * lane + 8); }
.LBB0_480:
	v_readlane_b32 s0, v252, 24
	v_lshlrev_b32_e32 v0, 10, v188
	s_waitcnt vmcnt(0)
	v_lshlrev_b32_e32 v2, 2, v188
	v_ashrrev_i32_e32 v189, 31, v188
	v_readlane_b32 s1, v252, 25
	v_and_b32_e32 v0, 0xc00, v0
	v_and_b32_e32 v2, 0x3f0, v2
	s_waitcnt lgkmcnt(0)
	v_lshl_add_u64 v[190:191], v[188:189], 4, s[0:1]
	v_add3_u32 v0, 0, v0, v2
	v_and_b32_e32 v18, 0xfffff00, v188
	v_lshl_add_u32 v209, v18, 4, v0
	v_add_u32_e32 v18, 0x200, v188
	v_and_b32_e32 v18, 0xfffff00, v18
	v_lshl_add_u32 v210, v18, 4, v0
	v_add_u32_e32 v18, 0x400, v188
	v_and_b32_e32 v18, 0xfffff00, v18
	v_lshl_add_u32 v211, v18, 4, v0
	v_add_u32_e32 v18, 0x600, v188
	v_and_b32_e32 v18, 0xfffff00, v18
	v_lshl_add_u32 v213, v18, 4, v0
	v_readlane_b32 s0, v252, 26
	v_ashrrev_i32_e32 v0, 6, v188
	v_mov_b32_e32 v212, v248
	v_and_b32_e32 v208, 63, v188
	v_bfe_u32 v2, v188, 3, 3
	v_or_b32_e32 v2, s0, v2
	v_readlane_b32 s0, v249, 3
	v_ashrrev_i32_e32 v3, 31, v2
	v_lshl_add_u64 v[192:193], v[2:3], 2, s[74:75]
	v_add_u32_e32 v189, s0, v0
	s_movk_i32 s0, 0x800
	v_cmp_gt_i32_e64 s[0:1], s0, v189
	v_readlane_b32 s2, v252, 32
	v_readlane_b32 s3, v252, 33
	v_readlane_b32 s4, v249, 61
	v_readlane_b32 s5, v249, 62
	s_mov_b32 s30, 0xcccccccc
	s_mov_b32 s31, 0xcccccccc
	s_mov_b32 s40, 0xaaaaaaaa
	s_mov_b32 s41, 0xaaaaaaaa
	v_lshlrev_b32_e32 v184, 14, v189
	v_lshl_add_u32 v184, v208, 5, v184
	v_lshrrev_b32_e32 v215, 8, v189
	v_mul_u32_u24_e32 v215, 0x6000, v215
	v_lshl_add_u32 v215, v208, 6, v215
	v_and_b32_e32 v216, 7, v208
	v_lshlrev_b32_e32 v217, 7, v189
	v_lshl_add_u32 v217, v216, 4, v217
	v_lshlrev_b32_e32 v246, 8, v189
	v_lshl_add_u32 v246, v216, 5, v246
	v_lshrrev_b32_e32 v216, 3, v208
	v_lshl_add_u32 v246, v216, 2, v246
	s_mov_b64 s[6:7], 0x2000
	v_lshl_add_u64 v[18:19], v[190:191], 0, s[6:7]
	s_mov_b64 s[6:7], 0x4000
	v_lshl_add_u64 v[20:21], v[190:191], 0, s[6:7]
	s_mov_b64 s[6:7], 0x6000
	v_lshl_add_u64 v[22:23], v[190:191], 0, s[6:7]
	global_load_dwordx4 v[2:5], v[190:191], off
	global_load_dwordx4 v[6:9], v[18:19], off
	global_load_dwordx4 v[10:13], v[20:21], off
	global_load_dwordx4 v[14:17], v[22:23], off
	s_and_saveexec_b64 s[38:39], s[0:1]
	global_load_dword v214, v[192:193], off
	global_load_dwordx4 v[130:133], v215, s[2:3]
	global_load_dwordx4 v[134:137], v215, s[2:3] offset:16
	global_load_dwordx4 v[138:141], v215, s[2:3] offset:32
	global_load_dwordx4 v[142:145], v215, s[2:3] offset:48
	global_load_dwordx4 v[178:181], v217, s[34:35]
	global_load_dwordx4 v[146:149], v184, s[94:95]
	global_load_dwordx4 v[150:153], v184, s[94:95] offset:16
	global_load_dwordx4 v[154:157], v184, s[94:95] offset:2048
	global_load_dwordx4 v[158:161], v184, s[94:95] offset:2064
	v_add_u32_e32 v184, 0x1000, v184
	global_load_dwordx4 v[162:165], v184, s[94:95]
	global_load_dwordx4 v[166:169], v184, s[94:95] offset:16
	global_load_dwordx4 v[170:173], v184, s[94:95] offset:2048
	global_load_dwordx4 v[174:177], v184, s[94:95] offset:2064
	v_add_u32_e32 v184, 0x1000, v184
	s_or_b64 exec, exec, s[38:39]
	s_cmp_lg_u64 s[0:1], 0
	s_cbranch_scc1 .Lfg_wv
	s_waitcnt vmcnt(0)
	s_branch .Lfg_wd
.Lfg_wv:
	s_waitcnt vmcnt(14)
.Lfg_wd:
	ds_write_b128 v209, v[2:5]
	ds_write_b128 v210, v[6:9]
	ds_write_b128 v211, v[10:13]
	ds_write_b128 v213, v[14:17]
	s_waitcnt lgkmcnt(0)
	s_barrier
	s_and_saveexec_b64 s[38:39], s[0:1]
	s_cbranch_execz .LBB0_493
	v_lshl_add_u32 v0, v208, 4, 0
	ds_read_b128 v[2:5], v0
	ds_read_b128 v[6:9], v0 offset:1024
	ds_read_b128 v[10:13], v0 offset:2048
	ds_read_b128 v[14:17], v0 offset:3072
	ds_read_b128 v[18:21], v0 offset:4096
	ds_read_b128 v[22:25], v0 offset:5120
	ds_read_b128 v[26:29], v0 offset:6144
	ds_read_b128 v[30:33], v0 offset:7168
	ds_read_b128 v[34:37], v0 offset:8192
	ds_read_b128 v[38:41], v0 offset:9216
	ds_read_b128 v[42:45], v0 offset:10240
	ds_read_b128 v[46:49], v0 offset:11264
	ds_read_b128 v[50:53], v0 offset:12288
	ds_read_b128 v[54:57], v0 offset:13312
	ds_read_b128 v[58:61], v0 offset:14336
	ds_read_b128 v[62:65], v0 offset:15360
	ds_read_b128 v[66:69], v0 offset:16384
	ds_read_b128 v[70:73], v0 offset:17408
	ds_read_b128 v[74:77], v0 offset:18432
	ds_read_b128 v[78:81], v0 offset:19456
	ds_read_b128 v[82:85], v0 offset:20480
	ds_read_b128 v[86:89], v0 offset:21504
	ds_read_b128 v[90:93], v0 offset:22528
	ds_read_b128 v[94:97], v0 offset:23552
	ds_read_b128 v[98:101], v0 offset:24576
	ds_read_b128 v[102:105], v0 offset:25600
	ds_read_b128 v[106:109], v0 offset:26624
	ds_read_b128 v[110:113], v0 offset:27648
	ds_read_b128 v[114:117], v0 offset:28672
	ds_read_b128 v[118:121], v0 offset:29696
	ds_read_b128 v[122:125], v0 offset:30720
	ds_read_b128 v[126:129], v0 offset:31744
	v_mov_b32_e32 v0, v189
; __device__ __forceinline__ void fg_tail(const Args& a, int l, LAS unsigned char* lds, const int tid) {
;     ...
;         for (int q = 0; q < 4; ++q) sh[q] = *(const f32x4*)(mod + (size_t)b * MODW + 16 * lane + 4 * q);
; #pragma unroll 1
;         for (int jb = 0; jb < 8; jb += 4) {
;             f32x4 rs4v[4]; u32x4 w0v[4], w1v[4];
; #pragma unroll
;             for (int j = 0; j < 4; ++j) { const int row = rowc + jb + j; rs4v[j] = *(const f32x4*)(rowss + (size_t)row * 4); w0v[j] = *(const u32x4*)(H + (size_t)row * DM + 16 * lane); w1v[j] = *(const u32x4*)(H + (size_t)row * DM + 16 * lane + 8); }
; #pragma unroll
;             for (int j = 0; j < 4; ++j) {
;                 const int row = rowc + jb + j;
;                 const f32x4 rs4 = rs4v[j]; const u32x4 w0 = w0v[j], w1 = w1v[j];
;                 const float r = 1.0f / sqrtf(((rs4[0] + rs4[1]) + (rs4[2] + rs4[3])) * (1.0f / 1024.0f) + EPS);
;                 float h[16];
; #pragma unroll
;                 for (int i = 0; i < 4; ++i) { h[2 * i] = __uint_as_float(w0[i] << 16); h[2 * i + 1] = __uint_as_float(w0[i] & 0xffff0000u); h[8 + 2 * i] = __uint_as_float(w1[i] << 16); h[8 + 2 * i + 1] = __uint_as_float(w1[i] & 0xffff0000u); }
; #pragma unroll
;                 for (int q = 0; q < 4; ++q) { h[4 * q] = h[4 * q] * r + sh[q][0]; h[4 * q + 1] = h[4 * q + 1] * r + sh[q][1]; h[4 * q + 2] = h[4 * q + 2] * r + sh[q][2]; h[4 * q + 3] = h[4 * q + 3] * r + sh[q][3]; }
;                 float d8[8];
; #pragma unroll
;                 for (int j8 = 0; j8 < 8; ++j8) { float acc = 0.f;
; #pragma unroll
;                     for (int q = 0; q < 4; ++q) { const f32x4 w = wl[(j8 * 4 + q) * 64 + lane]; acc += (h[4 * q] * w[0] + h[4 * q + 1] * w[1]) + (h[4 * q + 2] * w[2] + h[4 * q + 3] * w[3]); }
;                     d8[j8] = acc; }
;                 const float tot = reduce8(d8, lane);
.Lfg_loop:
	s_waitcnt vmcnt(8)
	v_add_f32_e32 v215, v178, v179
	v_add_f32_e32 v216, v180, v181
	v_add_f32_e32 v215, v215, v216
	v_fmamk_f32 v215, v215, 0x3a800000, v225
	v_mul_f32_e32 v216, 0x4f800000, v215
	v_cmp_gt_f32_e32 vcc, s16, v215
	s_nop 1
	v_cndmask_b32_e32 v215, v215, v216, vcc
	v_sqrt_f32_e32 v216, v215
	s_nop 0
	v_add_u32_e32 v217, -1, v216
	v_add_u32_e32 v218, 1, v216
	v_fma_f32 v228, -v217, v216, v215
	v_fma_f32 v187, -v218, v216, v215
	v_cmp_ge_f32_e64 s[10:11], 0, v228
	s_nop 1
	v_cndmask_b32_e64 v241, v216, v217, s[10:11]
	v_cmp_lt_f32_e64 s[10:11], 0, v187
	s_nop 1
	v_cndmask_b32_e64 v187, v241, v218, s[10:11]
	v_mul_f32_e32 v241, 0x37800000, v187
	v_cndmask_b32_e32 v187, v187, v241, vcc
	v_cmp_class_f32_e32 vcc, v215, v226
	s_nop 1
	v_cndmask_b32_e32 v187, v187, v215, vcc
	v_div_scale_f32 v241, s[10:11], v187, v187, 1.0
	v_rcp_f32_e32 v215, v241
	v_div_scale_f32 v218, vcc, 1.0, v187, 1.0
	v_fma_f32 v216, -v241, v215, 1.0
	v_fmac_f32_e32 v215, v216, v215
	v_mul_f32_e32 v216, v218, v215
	v_fma_f32 v228, -v241, v216, v218
	v_fmac_f32_e32 v216, v228, v215
	v_fma_f32 v241, -v241, v216, v218
	v_div_fmas_f32 v241, v241, v215, v216
	v_div_fixup_f32 v247, v241, v187, 1.0
	s_waitcnt lgkmcnt(0)
	v_pk_mul_f32 v[194:195], v[130:131], v[2:3]
	v_pk_mul_f32 v[196:197], v[130:131], v[18:19]
	v_pk_mul_f32 v[198:199], v[130:131], v[34:35]
	v_pk_mul_f32 v[200:201], v[130:131], v[50:51]
	v_pk_mul_f32 v[202:203], v[130:131], v[66:67]
	v_pk_mul_f32 v[204:205], v[130:131], v[82:83]
	v_pk_mul_f32 v[206:207], v[130:131], v[98:99]
	v_pk_mul_f32 v[182:183], v[130:131], v[114:115]
	v_pk_fma_f32 v[194:195], v[132:133], v[4:5], v[194:195]
	v_pk_fma_f32 v[196:197], v[132:133], v[20:21], v[196:197]
	v_pk_fma_f32 v[198:199], v[132:133], v[36:37], v[198:199]
	v_pk_fma_f32 v[200:201], v[132:133], v[52:53], v[200:201]
	v_pk_fma_f32 v[202:203], v[132:133], v[68:69], v[202:203]
	v_pk_fma_f32 v[204:205], v[132:133], v[84:85], v[204:205]
	v_pk_fma_f32 v[206:207], v[132:133], v[100:101], v[206:207]
	v_pk_fma_f32 v[182:183], v[132:133], v[116:117], v[182:183]
	v_pk_fma_f32 v[194:195], v[134:135], v[6:7], v[194:195]
	v_pk_fma_f32 v[196:197], v[134:135], v[22:23], v[196:197]
	v_pk_fma_f32 v[198:199], v[134:135], v[38:39], v[198:199]
	v_pk_fma_f32 v[200:201], v[134:135], v[54:55], v[200:201]
	v_pk_fma_f32 v[202:203], v[134:135], v[70:71], v[202:203]
	v_pk_fma_f32 v[204:205], v[134:135], v[86:87], v[204:205]
	v_pk_fma_f32 v[206:207], v[134:135], v[102:103], v[206:207]
	v_pk_fma_f32 v[182:183], v[134:135], v[118:119], v[182:183]
	v_pk_fma_f32 v[194:195], v[136:137], v[8:9], v[194:195]
	v_pk_fma_f32 v[196:197], v[136:137], v[24:25], v[196:197]
	v_pk_fma_f32 v[198:199], v[136:137], v[40:41], v[198:199]
	v_pk_fma_f32 v[200:201], v[136:137], v[56:57], v[200:201]
	v_pk_fma_f32 v[202:203], v[136:137], v[72:73], v[202:203]
	v_pk_fma_f32 v[204:205], v[136:137], v[88:89], v[204:205]
	v_pk_fma_f32 v[206:207], v[136:137], v[104:105], v[206:207]
	v_pk_fma_f32 v[182:183], v[136:137], v[120:121], v[182:183]
	v_pk_fma_f32 v[194:195], v[138:139], v[10:11], v[194:195]
	v_pk_fma_f32 v[196:197], v[138:139], v[26:27], v[196:197]
	v_pk_fma_f32 v[198:199], v[138:139], v[42:43], v[198:199]
	v_pk_fma_f32 v[200:201], v[138:139], v[58:59], v[200:201]
	v_pk_fma_f32 v[202:203], v[138:139], v[74:75], v[202:203]
	v_pk_fma_f32 v[204:205], v[138:139], v[90:91], v[204:205]
	v_pk_fma_f32 v[206:207], v[138:139], v[106:107], v[206:207]
	v_pk_fma_f32 v[182:183], v[138:139], v[122:123], v[182:183]
	v_pk_fma_f32 v[194:195], v[140:141], v[12:13], v[194:195]
	v_pk_fma_f32 v[196:197], v[140:141], v[28:29], v[196:197]
	v_pk_fma_f32 v[198:199], v[140:141], v[44:45], v[198:199]
	v_pk_fma_f32 v[200:201], v[140:141], v[60:61], v[200:201]
	v_pk_fma_f32 v[202:203], v[140:141], v[76:77], v[202:203]
	v_pk_fma_f32 v[204:205], v[140:141], v[92:93], v[204:205]
	v_pk_fma_f32 v[206:207], v[140:141], v[108:109], v[206:207]
	v_pk_fma_f32 v[182:183], v[140:141], v[124:125], v[182:183]
	v_pk_fma_f32 v[194:195], v[142:143], v[14:15], v[194:195]
	v_pk_fma_f32 v[196:197], v[142:143], v[30:31], v[196:197]
	v_pk_fma_f32 v[198:199], v[142:143], v[46:47], v[198:199]
	v_pk_fma_f32 v[200:201], v[142:143], v[62:63], v[200:201]
	v_pk_fma_f32 v[202:203], v[142:143], v[78:79], v[202:203]
	v_pk_fma_f32 v[204:205], v[142:143], v[94:95], v[204:205]
	v_pk_fma_f32 v[206:207], v[142:143], v[110:111], v[206:207]
	v_pk_fma_f32 v[182:183], v[142:143], v[126:127], v[182:183]
	v_pk_fma_f32 v[194:195], v[144:145], v[16:17], v[194:195]
	v_pk_fma_f32 v[196:197], v[144:145], v[32:33], v[196:197]
	v_pk_fma_f32 v[198:199], v[144:145], v[48:49], v[198:199]
	v_pk_fma_f32 v[200:201], v[144:145], v[64:65], v[200:201]
	v_pk_fma_f32 v[202:203], v[144:145], v[80:81], v[202:203]
	v_pk_fma_f32 v[204:205], v[144:145], v[96:97], v[204:205]
	v_pk_fma_f32 v[206:207], v[144:145], v[112:113], v[206:207]
	v_pk_fma_f32 v[182:183], v[144:145], v[128:129], v[182:183]
	v_add_f32_e32 v194, v194, v195
	v_add_f32_e32 v196, v196, v197
	v_add_f32_e32 v198, v198, v199
	v_add_f32_e32 v200, v200, v201
	v_add_f32_e32 v202, v202, v203
	v_add_f32_e32 v204, v204, v205
	v_add_f32_e32 v206, v206, v207
	v_add_f32_e32 v182, v182, v183
	s_nop 1
	v_permlane32_swap_b32_e32 v194, v202
	v_permlane32_swap_b32_e32 v196, v204
	v_permlane32_swap_b32_e32 v198, v206
	v_permlane32_swap_b32_e32 v200, v182
	v_add_f32_e32 v194, v194, v202
	v_add_f32_e32 v196, v196, v204
	v_add_f32_e32 v198, v198, v206
	v_add_f32_e32 v200, v200, v182
	s_nop 1
	v_permlane16_swap_b32_e32 v194, v198
	v_permlane16_swap_b32_e32 v196, v200
	v_add_f32_e32 v194, v194, v198
	v_add_f32_e32 v196, v196, v200
	s_nop 1
	v_add_f32_dpp v248, v194, v194 row_ror:8 row_mask:0xf bank_mask:0x3
	v_add_f32_dpp v248, v196, v196 row_ror:8 row_mask:0xf bank_mask:0xc
	s_nop 1
	v_add_f32_dpp v248, v248, v248 quad_perm:[1,0,3,2] row_mask:0xf bank_mask:0xf
	s_nop 1
	v_add_f32_dpp v248, v248, v248 quad_perm:[2,3,0,1] row_mask:0xf bank_mask:0xf
	s_nop 1
	v_add_f32_dpp v248, v248, v248 row_half_mirror row_mask:0xf bank_mask:0xf
	v_add_f32_e32 v248, v248, v214
	s_waitcnt vmcnt(6)
; __device__ __forceinline__ void fg_tail(const Args& a, int l, LAS unsigned char* lds, const int tid) {
;     ...
;             for (int j = 0; j < 4; ++j) { const int row = rowc + jb + j; rs4v[j] = *(const f32x4*)(rowss + (size_t)row * 4); w0v[j] = *(const u32x4*)(H + (size_t)row * DM + 16 * lane); w1v[j] = *(const u32x4*)(H + (size_t)row * DM + 16 * lane + 8); }
; #pragma unroll
;             for (int j = 0; j < 4; ++j) {
;                 const int row = rowc + jb + j;
;                 const f32x4 rs4 = rs4v[j]; const u32x4 w0 = w0v[j], w1 = w1v[j];
;                 const float r = 1.0f / sqrtf(((rs4[0] + rs4[1]) + (rs4[2] + rs4[3])) * (1.0f / 1024.0f) + EPS);
;                 float h[16];
; #pragma unroll
;                 for (int i = 0; i < 4; ++i) { h[2 * i] = __uint_as_float(w0[i] << 16); h[2 * i + 1] = __uint_as_float(w0[i] & 0xffff0000u); h[8 + 2 * i] = __uint_as_float(w1[i] << 16); h[8 + 2 * i + 1] = __uint_as_float(w1[i] & 0xffff0000u); }
; #pragma unroll
;                 for (int q = 0; q < 4; ++q) { h[4 * q] = h[4 * q] * r + sh[q][0]; h[4 * q + 1] = h[4 * q + 1] * r + sh[q][1]; h[4 * q + 2] = h[4 * q + 2] * r + sh[q][2]; h[4 * q + 3] = h[4 * q + 3] * r + sh[q][3]; }
;                 float d8[8];
; #pragma unroll
;                 for (int j8 = 0; j8 < 8; ++j8) { float acc = 0.f;
; #pragma unroll
;                     for (int q = 0; q < 4; ++q) { const f32x4 w = wl[(j8 * 4 + q) * 64 + lane]; acc += (h[4 * q] * w[0] + h[4 * q + 1] * w[1]) + (h[4 * q + 2] * w[2] + h[4 * q + 3] * w[3]); }
;                     d8[j8] = acc; }
;                 const float tot = reduce8(d8, lane);
	v_lshlrev_b32_e32 v130, 16, v146
	v_and_b32_e32 v131, 0xffff0000, v146
	v_lshlrev_b32_e32 v132, 16, v147
	v_and_b32_e32 v133, 0xffff0000, v147
	v_lshlrev_b32_e32 v134, 16, v148
	v_and_b32_e32 v135, 0xffff0000, v148
	v_lshlrev_b32_e32 v136, 16, v149
	v_and_b32_e32 v137, 0xffff0000, v149
	v_lshlrev_b32_e32 v138, 16, v150
	v_and_b32_e32 v139, 0xffff0000, v150
	v_lshlrev_b32_e32 v140, 16, v151
	v_and_b32_e32 v141, 0xffff0000, v151
	v_lshlrev_b32_e32 v142, 16, v152
	v_and_b32_e32 v143, 0xffff0000, v152
	v_lshlrev_b32_e32 v144, 16, v153
	v_and_b32_e32 v145, 0xffff0000, v153
	global_load_dwordx4 v[146:149], v184, s[94:95]
	global_load_dwordx4 v[150:153], v184, s[94:95] offset:16
	v_pk_mul_f32 v[194:195], v[130:131], v[2:3]
	v_pk_mul_f32 v[196:197], v[130:131], v[18:19]
	v_pk_mul_f32 v[198:199], v[130:131], v[34:35]
	v_pk_mul_f32 v[200:201], v[130:131], v[50:51]
	v_pk_mul_f32 v[202:203], v[130:131], v[66:67]
	v_pk_mul_f32 v[204:205], v[130:131], v[82:83]
	v_pk_mul_f32 v[206:207], v[130:131], v[98:99]
	v_pk_mul_f32 v[182:183], v[130:131], v[114:115]
	v_pk_fma_f32 v[194:195], v[132:133], v[4:5], v[194:195]
	v_pk_fma_f32 v[196:197], v[132:133], v[20:21], v[196:197]
	v_pk_fma_f32 v[198:199], v[132:133], v[36:37], v[198:199]
	v_pk_fma_f32 v[200:201], v[132:133], v[52:53], v[200:201]
	v_pk_fma_f32 v[202:203], v[132:133], v[68:69], v[202:203]
	v_pk_fma_f32 v[204:205], v[132:133], v[84:85], v[204:205]
	v_pk_fma_f32 v[206:207], v[132:133], v[100:101], v[206:207]
	v_pk_fma_f32 v[182:183], v[132:133], v[116:117], v[182:183]
	v_pk_fma_f32 v[194:195], v[134:135], v[6:7], v[194:195]
	v_pk_fma_f32 v[196:197], v[134:135], v[22:23], v[196:197]
	v_pk_fma_f32 v[198:199], v[134:135], v[38:39], v[198:199]
	v_pk_fma_f32 v[200:201], v[134:135], v[54:55], v[200:201]
	v_pk_fma_f32 v[202:203], v[134:135], v[70:71], v[202:203]
	v_pk_fma_f32 v[204:205], v[134:135], v[86:87], v[204:205]
	v_pk_fma_f32 v[206:207], v[134:135], v[102:103], v[206:207]
	v_pk_fma_f32 v[182:183], v[134:135], v[118:119], v[182:183]
	v_pk_fma_f32 v[194:195], v[136:137], v[8:9], v[194:195]
	v_pk_fma_f32 v[196:197], v[136:137], v[24:25], v[196:197]
	v_pk_fma_f32 v[198:199], v[136:137], v[40:41], v[198:199]
	v_pk_fma_f32 v[200:201], v[136:137], v[56:57], v[200:201]
	v_pk_fma_f32 v[202:203], v[136:137], v[72:73], v[202:203]
	v_pk_fma_f32 v[204:205], v[136:137], v[88:89], v[204:205]
	v_pk_fma_f32 v[206:207], v[136:137], v[104:105], v[206:207]
	v_pk_fma_f32 v[182:183], v[136:137], v[120:121], v[182:183]
	v_pk_fma_f32 v[194:195], v[138:139], v[10:11], v[194:195]
	v_pk_fma_f32 v[196:197], v[138:139], v[26:27], v[196:197]
	v_pk_fma_f32 v[198:199], v[138:139], v[42:43], v[198:199]
	v_pk_fma_f32 v[200:201], v[138:139], v[58:59], v[200:201]
	v_pk_fma_f32 v[202:203], v[138:139], v[74:75], v[202:203]
	v_pk_fma_f32 v[204:205], v[138:139], v[90:91], v[204:205]
	v_pk_fma_f32 v[206:207], v[138:139], v[106:107], v[206:207]
	v_pk_fma_f32 v[182:183], v[138:139], v[122:123], v[182:183]
	v_pk_fma_f32 v[194:195], v[140:141], v[12:13], v[194:195]
	v_pk_fma_f32 v[196:197], v[140:141], v[28:29], v[196:197]
	v_pk_fma_f32 v[198:199], v[140:141], v[44:45], v[198:199]
	v_pk_fma_f32 v[200:201], v[140:141], v[60:61], v[200:201]
	v_pk_fma_f32 v[202:203], v[140:141], v[76:77], v[202:203]
	v_pk_fma_f32 v[204:205], v[140:141], v[92:93], v[204:205]
	v_pk_fma_f32 v[206:207], v[140:141], v[108:109], v[206:207]
	v_pk_fma_f32 v[182:183], v[140:141], v[124:125], v[182:183]
	v_pk_fma_f32 v[194:195], v[142:143], v[14:15], v[194:195]
	v_pk_fma_f32 v[196:197], v[142:143], v[30:31], v[196:197]
	v_pk_fma_f32 v[198:199], v[142:143], v[46:47], v[198:199]
	v_pk_fma_f32 v[200:201], v[142:143], v[62:63], v[200:201]
	v_pk_fma_f32 v[202:203], v[142:143], v[78:79], v[202:203]
	v_pk_fma_f32 v[204:205], v[142:143], v[94:95], v[204:205]
	v_pk_fma_f32 v[206:207], v[142:143], v[110:111], v[206:207]
	v_pk_fma_f32 v[182:183], v[142:143], v[126:127], v[182:183]
	v_pk_fma_f32 v[194:195], v[144:145], v[16:17], v[194:195]
	v_pk_fma_f32 v[196:197], v[144:145], v[32:33], v[196:197]
	v_pk_fma_f32 v[198:199], v[144:145], v[48:49], v[198:199]
	v_pk_fma_f32 v[200:201], v[144:145], v[64:65], v[200:201]
	v_pk_fma_f32 v[202:203], v[144:145], v[80:81], v[202:203]
	v_pk_fma_f32 v[204:205], v[144:145], v[96:97], v[204:205]
	v_pk_fma_f32 v[206:207], v[144:145], v[112:113], v[206:207]
	v_pk_fma_f32 v[182:183], v[144:145], v[128:129], v[182:183]
	v_add_f32_e32 v194, v194, v195
	v_add_f32_e32 v196, v196, v197
	v_add_f32_e32 v198, v198, v199
	v_add_f32_e32 v200, v200, v201
	v_add_f32_e32 v202, v202, v203
	v_add_f32_e32 v204, v204, v205
	v_add_f32_e32 v206, v206, v207
	v_add_f32_e32 v182, v182, v183
	s_nop 1
	v_permlane32_swap_b32_e32 v194, v202
	v_permlane32_swap_b32_e32 v196, v204
	v_permlane32_swap_b32_e32 v198, v206
	v_permlane32_swap_b32_e32 v200, v182
	v_add_f32_e32 v194, v194, v202
	v_add_f32_e32 v196, v196, v204
	v_add_f32_e32 v198, v198, v206
	v_add_f32_e32 v200, v200, v182
	s_nop 1
	v_permlane16_swap_b32_e32 v194, v198
	v_permlane16_swap_b32_e32 v196, v200
	v_add_f32_e32 v194, v194, v198
	v_add_f32_e32 v196, v196, v200
	s_nop 1
	v_add_f32_dpp v233, v194, v194 row_ror:8 row_mask:0xf bank_mask:0x3
	v_add_f32_dpp v233, v196, v196 row_ror:8 row_mask:0xf bank_mask:0xc
	s_waitcnt vmcnt(6)
; __device__ __forceinline__ void fg_tail(const Args& a, int l, LAS unsigned char* lds, const int tid) {
;     ...
;             for (int j = 0; j < 4; ++j) { const int row = rowc + jb + j; rs4v[j] = *(const f32x4*)(rowss + (size_t)row * 4); w0v[j] = *(const u32x4*)(H + (size_t)row * DM + 16 * lane); w1v[j] = *(const u32x4*)(H + (size_t)row * DM + 16 * lane + 8); }
; #pragma unroll
;             for (int j = 0; j < 4; ++j) {
;                 const int row = rowc + jb + j;
;                 const f32x4 rs4 = rs4v[j]; const u32x4 w0 = w0v[j], w1 = w1v[j];
;                 const float r = 1.0f / sqrtf(((rs4[0] + rs4[1]) + (rs4[2] + rs4[3])) * (1.0f / 1024.0f) + EPS);
;                 float h[16];
; #pragma unroll
;                 for (int i = 0; i < 4; ++i) { h[2 * i] = __uint_as_float(w0[i] << 16); h[2 * i + 1] = __uint_as_float(w0[i] & 0xffff0000u); h[8 + 2 * i] = __uint_as_float(w1[i] << 16); h[8 + 2 * i + 1] = __uint_as_float(w1[i] & 0xffff0000u); }
; #pragma unroll
;                 for (int q = 0; q < 4; ++q) { h[4 * q] = h[4 * q] * r + sh[q][0]; h[4 * q + 1] = h[4 * q + 1] * r + sh[q][1]; h[4 * q + 2] = h[4 * q + 2] * r + sh[q][2]; h[4 * q + 3] = h[4 * q + 3] * r + sh[q][3]; }
;                 float d8[8];
; #pragma unroll
;                 for (int j8 = 0; j8 < 8; ++j8) { float acc = 0.f;
; #pragma unroll
;                     for (int q = 0; q < 4; ++q) { const f32x4 w = wl[(j8 * 4 + q) * 64 + lane]; acc += (h[4 * q] * w[0] + h[4 * q + 1] * w[1]) + (h[4 * q + 2] * w[2] + h[4 * q + 3] * w[3]); }
;                     d8[j8] = acc; }
;                 const float tot = reduce8(d8, lane);
	v_lshlrev_b32_e32 v130, 16, v154
	v_and_b32_e32 v131, 0xffff0000, v154
	v_lshlrev_b32_e32 v132, 16, v155
	v_and_b32_e32 v133, 0xffff0000, v155
	v_lshlrev_b32_e32 v134, 16, v156
	v_and_b32_e32 v135, 0xffff0000, v156
	v_lshlrev_b32_e32 v136, 16, v157
	v_and_b32_e32 v137, 0xffff0000, v157
	v_lshlrev_b32_e32 v138, 16, v158
	v_and_b32_e32 v139, 0xffff0000, v158
	v_lshlrev_b32_e32 v140, 16, v159
	v_and_b32_e32 v141, 0xffff0000, v159
	v_lshlrev_b32_e32 v142, 16, v160
	v_and_b32_e32 v143, 0xffff0000, v160
	v_lshlrev_b32_e32 v144, 16, v161
	v_and_b32_e32 v145, 0xffff0000, v161
	global_load_dwordx4 v[154:157], v184, s[94:95] offset:2048
	global_load_dwordx4 v[158:161], v184, s[94:95] offset:2064
	v_add_u32_e32 v184, 0x1000, v184
	v_pk_mul_f32 v[194:195], v[130:131], v[2:3]
	v_pk_mul_f32 v[196:197], v[130:131], v[18:19]
	v_pk_mul_f32 v[198:199], v[130:131], v[34:35]
	v_pk_mul_f32 v[200:201], v[130:131], v[50:51]
	v_pk_mul_f32 v[202:203], v[130:131], v[66:67]
	v_pk_mul_f32 v[204:205], v[130:131], v[82:83]
	v_pk_mul_f32 v[206:207], v[130:131], v[98:99]
	v_pk_mul_f32 v[182:183], v[130:131], v[114:115]
	v_pk_fma_f32 v[194:195], v[132:133], v[4:5], v[194:195]
	v_pk_fma_f32 v[196:197], v[132:133], v[20:21], v[196:197]
	v_pk_fma_f32 v[198:199], v[132:133], v[36:37], v[198:199]
	v_pk_fma_f32 v[200:201], v[132:133], v[52:53], v[200:201]
	v_pk_fma_f32 v[202:203], v[132:133], v[68:69], v[202:203]
	v_pk_fma_f32 v[204:205], v[132:133], v[84:85], v[204:205]
	v_pk_fma_f32 v[206:207], v[132:133], v[100:101], v[206:207]
	v_pk_fma_f32 v[182:183], v[132:133], v[116:117], v[182:183]
	v_pk_fma_f32 v[194:195], v[134:135], v[6:7], v[194:195]
	v_pk_fma_f32 v[196:197], v[134:135], v[22:23], v[196:197]
	v_pk_fma_f32 v[198:199], v[134:135], v[38:39], v[198:199]
	v_pk_fma_f32 v[200:201], v[134:135], v[54:55], v[200:201]
	v_pk_fma_f32 v[202:203], v[134:135], v[70:71], v[202:203]
	v_pk_fma_f32 v[204:205], v[134:135], v[86:87], v[204:205]
	v_pk_fma_f32 v[206:207], v[134:135], v[102:103], v[206:207]
	v_pk_fma_f32 v[182:183], v[134:135], v[118:119], v[182:183]
	v_pk_fma_f32 v[194:195], v[136:137], v[8:9], v[194:195]
	v_pk_fma_f32 v[196:197], v[136:137], v[24:25], v[196:197]
	v_pk_fma_f32 v[198:199], v[136:137], v[40:41], v[198:199]
	v_pk_fma_f32 v[200:201], v[136:137], v[56:57], v[200:201]
	v_pk_fma_f32 v[202:203], v[136:137], v[72:73], v[202:203]
	v_pk_fma_f32 v[204:205], v[136:137], v[88:89], v[204:205]
	v_pk_fma_f32 v[206:207], v[136:137], v[104:105], v[206:207]
	v_pk_fma_f32 v[182:183], v[136:137], v[120:121], v[182:183]
	v_pk_fma_f32 v[194:195], v[138:139], v[10:11], v[194:195]
	v_pk_fma_f32 v[196:197], v[138:139], v[26:27], v[196:197]
	v_pk_fma_f32 v[198:199], v[138:139], v[42:43], v[198:199]
	v_pk_fma_f32 v[200:201], v[138:139], v[58:59], v[200:201]
	v_pk_fma_f32 v[202:203], v[138:139], v[74:75], v[202:203]
	v_pk_fma_f32 v[204:205], v[138:139], v[90:91], v[204:205]
	v_pk_fma_f32 v[206:207], v[138:139], v[106:107], v[206:207]
	v_pk_fma_f32 v[182:183], v[138:139], v[122:123], v[182:183]
	v_pk_fma_f32 v[194:195], v[140:141], v[12:13], v[194:195]
	v_pk_fma_f32 v[196:197], v[140:141], v[28:29], v[196:197]
	v_pk_fma_f32 v[198:199], v[140:141], v[44:45], v[198:199]
	v_pk_fma_f32 v[200:201], v[140:141], v[60:61], v[200:201]
	v_pk_fma_f32 v[202:203], v[140:141], v[76:77], v[202:203]
	v_pk_fma_f32 v[204:205], v[140:141], v[92:93], v[204:205]
	v_pk_fma_f32 v[206:207], v[140:141], v[108:109], v[206:207]
	v_pk_fma_f32 v[182:183], v[140:141], v[124:125], v[182:183]
	v_pk_fma_f32 v[194:195], v[142:143], v[14:15], v[194:195]
	v_pk_fma_f32 v[196:197], v[142:143], v[30:31], v[196:197]
	v_pk_fma_f32 v[198:199], v[142:143], v[46:47], v[198:199]
	v_pk_fma_f32 v[200:201], v[142:143], v[62:63], v[200:201]
	v_pk_fma_f32 v[202:203], v[142:143], v[78:79], v[202:203]
	v_pk_fma_f32 v[204:205], v[142:143], v[94:95], v[204:205]
	v_pk_fma_f32 v[206:207], v[142:143], v[110:111], v[206:207]
	v_pk_fma_f32 v[182:183], v[142:143], v[126:127], v[182:183]
	v_pk_fma_f32 v[194:195], v[144:145], v[16:17], v[194:195]
	v_pk_fma_f32 v[196:197], v[144:145], v[32:33], v[196:197]
	v_pk_fma_f32 v[198:199], v[144:145], v[48:49], v[198:199]
	v_pk_fma_f32 v[200:201], v[144:145], v[64:65], v[200:201]
	v_pk_fma_f32 v[202:203], v[144:145], v[80:81], v[202:203]
	v_pk_fma_f32 v[204:205], v[144:145], v[96:97], v[204:205]
	v_pk_fma_f32 v[206:207], v[144:145], v[112:113], v[206:207]
	v_pk_fma_f32 v[182:183], v[144:145], v[128:129], v[182:183]
	v_add_f32_e32 v194, v194, v195
	v_add_f32_e32 v196, v196, v197
	v_add_f32_e32 v198, v198, v199
	v_add_f32_e32 v200, v200, v201
	v_add_f32_e32 v202, v202, v203
	v_add_f32_e32 v204, v204, v205
	v_add_f32_e32 v206, v206, v207
	v_add_f32_e32 v182, v182, v183
	s_nop 1
	v_permlane32_swap_b32_e32 v194, v202
	v_permlane32_swap_b32_e32 v196, v204
	v_permlane32_swap_b32_e32 v198, v206
	v_permlane32_swap_b32_e32 v200, v182
	v_add_f32_e32 v194, v194, v202
	v_add_f32_e32 v196, v196, v204
	v_add_f32_e32 v198, v198, v206
	v_add_f32_e32 v200, v200, v182
	s_nop 1
	v_permlane16_swap_b32_e32 v194, v198
	v_permlane16_swap_b32_e32 v196, v200
	v_add_f32_e32 v194, v194, v198
	v_add_f32_e32 v196, v196, v200
	s_nop 1
	v_add_f32_dpp v234, v194, v194 row_ror:8 row_mask:0xf bank_mask:0x3
	v_add_f32_dpp v234, v196, v196 row_ror:8 row_mask:0xf bank_mask:0xc
	s_waitcnt vmcnt(6)
; __device__ __forceinline__ void fg_tail(const Args& a, int l, LAS unsigned char* lds, const int tid) {
;     ...
;             for (int j = 0; j < 4; ++j) { const int row = rowc + jb + j; rs4v[j] = *(const f32x4*)(rowss + (size_t)row * 4); w0v[j] = *(const u32x4*)(H + (size_t)row * DM + 16 * lane); w1v[j] = *(const u32x4*)(H + (size_t)row * DM + 16 * lane + 8); }
; #pragma unroll
;             for (int j = 0; j < 4; ++j) {
;                 const int row = rowc + jb + j;
;                 const f32x4 rs4 = rs4v[j]; const u32x4 w0 = w0v[j], w1 = w1v[j];
;                 const float r = 1.0f / sqrtf(((rs4[0] + rs4[1]) + (rs4[2] + rs4[3])) * (1.0f / 1024.0f) + EPS);
;                 float h[16];
; #pragma unroll
;                 for (int i = 0; i < 4; ++i) { h[2 * i] = __uint_as_float(w0[i] << 16); h[2 * i + 1] = __uint_as_float(w0[i] & 0xffff0000u); h[8 + 2 * i] = __uint_as_float(w1[i] << 16); h[8 + 2 * i + 1] = __uint_as_float(w1[i] & 0xffff0000u); }
; #pragma unroll
;                 for (int q = 0; q < 4; ++q) { h[4 * q] = h[4 * q] * r + sh[q][0]; h[4 * q + 1] = h[4 * q + 1] * r + sh[q][1]; h[4 * q + 2] = h[4 * q + 2] * r + sh[q][2]; h[4 * q + 3] = h[4 * q + 3] * r + sh[q][3]; }
;                 float d8[8];
; #pragma unroll
;                 for (int j8 = 0; j8 < 8; ++j8) { float acc = 0.f;
; #pragma unroll
;                     for (int q = 0; q < 4; ++q) { const f32x4 w = wl[(j8 * 4 + q) * 64 + lane]; acc += (h[4 * q] * w[0] + h[4 * q + 1] * w[1]) + (h[4 * q + 2] * w[2] + h[4 * q + 3] * w[3]); }
;                     d8[j8] = acc; }
;                 const float tot = reduce8(d8, lane);
	v_lshlrev_b32_e32 v130, 16, v162
	v_and_b32_e32 v131, 0xffff0000, v162
	v_lshlrev_b32_e32 v132, 16, v163
	v_and_b32_e32 v133, 0xffff0000, v163
	v_lshlrev_b32_e32 v134, 16, v164
	v_and_b32_e32 v135, 0xffff0000, v164
	v_lshlrev_b32_e32 v136, 16, v165
	v_and_b32_e32 v137, 0xffff0000, v165
	v_lshlrev_b32_e32 v138, 16, v166
	v_and_b32_e32 v139, 0xffff0000, v166
	v_lshlrev_b32_e32 v140, 16, v167
	v_and_b32_e32 v141, 0xffff0000, v167
	v_lshlrev_b32_e32 v142, 16, v168
	v_and_b32_e32 v143, 0xffff0000, v168
	v_lshlrev_b32_e32 v144, 16, v169
	v_and_b32_e32 v145, 0xffff0000, v169
	global_load_dwordx4 v[162:165], v184, s[94:95]
	global_load_dwordx4 v[166:169], v184, s[94:95] offset:16
	v_pk_mul_f32 v[194:195], v[130:131], v[2:3]
	v_pk_mul_f32 v[196:197], v[130:131], v[18:19]
	v_pk_mul_f32 v[198:199], v[130:131], v[34:35]
	v_pk_mul_f32 v[200:201], v[130:131], v[50:51]
	v_pk_mul_f32 v[202:203], v[130:131], v[66:67]
	v_pk_mul_f32 v[204:205], v[130:131], v[82:83]
	v_pk_mul_f32 v[206:207], v[130:131], v[98:99]
	v_pk_mul_f32 v[182:183], v[130:131], v[114:115]
	v_pk_fma_f32 v[194:195], v[132:133], v[4:5], v[194:195]
	v_pk_fma_f32 v[196:197], v[132:133], v[20:21], v[196:197]
	v_pk_fma_f32 v[198:199], v[132:133], v[36:37], v[198:199]
	v_pk_fma_f32 v[200:201], v[132:133], v[52:53], v[200:201]
	v_pk_fma_f32 v[202:203], v[132:133], v[68:69], v[202:203]
	v_pk_fma_f32 v[204:205], v[132:133], v[84:85], v[204:205]
	v_pk_fma_f32 v[206:207], v[132:133], v[100:101], v[206:207]
	v_pk_fma_f32 v[182:183], v[132:133], v[116:117], v[182:183]
	v_pk_fma_f32 v[194:195], v[134:135], v[6:7], v[194:195]
	v_pk_fma_f32 v[196:197], v[134:135], v[22:23], v[196:197]
	v_pk_fma_f32 v[198:199], v[134:135], v[38:39], v[198:199]
	v_pk_fma_f32 v[200:201], v[134:135], v[54:55], v[200:201]
	v_pk_fma_f32 v[202:203], v[134:135], v[70:71], v[202:203]
	v_pk_fma_f32 v[204:205], v[134:135], v[86:87], v[204:205]
	v_pk_fma_f32 v[206:207], v[134:135], v[102:103], v[206:207]
	v_pk_fma_f32 v[182:183], v[134:135], v[118:119], v[182:183]
	v_pk_fma_f32 v[194:195], v[136:137], v[8:9], v[194:195]
	v_pk_fma_f32 v[196:197], v[136:137], v[24:25], v[196:197]
	v_pk_fma_f32 v[198:199], v[136:137], v[40:41], v[198:199]
	v_pk_fma_f32 v[200:201], v[136:137], v[56:57], v[200:201]
	v_pk_fma_f32 v[202:203], v[136:137], v[72:73], v[202:203]
	v_pk_fma_f32 v[204:205], v[136:137], v[88:89], v[204:205]
	v_pk_fma_f32 v[206:207], v[136:137], v[104:105], v[206:207]
	v_pk_fma_f32 v[182:183], v[136:137], v[120:121], v[182:183]
	v_pk_fma_f32 v[194:195], v[138:139], v[10:11], v[194:195]
	v_pk_fma_f32 v[196:197], v[138:139], v[26:27], v[196:197]
	v_pk_fma_f32 v[198:199], v[138:139], v[42:43], v[198:199]
	v_pk_fma_f32 v[200:201], v[138:139], v[58:59], v[200:201]
	v_pk_fma_f32 v[202:203], v[138:139], v[74:75], v[202:203]
	v_pk_fma_f32 v[204:205], v[138:139], v[90:91], v[204:205]
	v_pk_fma_f32 v[206:207], v[138:139], v[106:107], v[206:207]
	v_pk_fma_f32 v[182:183], v[138:139], v[122:123], v[182:183]
	v_pk_fma_f32 v[194:195], v[140:141], v[12:13], v[194:195]
	v_pk_fma_f32 v[196:197], v[140:141], v[28:29], v[196:197]
	v_pk_fma_f32 v[198:199], v[140:141], v[44:45], v[198:199]
	v_pk_fma_f32 v[200:201], v[140:141], v[60:61], v[200:201]
	v_pk_fma_f32 v[202:203], v[140:141], v[76:77], v[202:203]
	v_pk_fma_f32 v[204:205], v[140:141], v[92:93], v[204:205]
	v_pk_fma_f32 v[206:207], v[140:141], v[108:109], v[206:207]
	v_pk_fma_f32 v[182:183], v[140:141], v[124:125], v[182:183]
	v_pk_fma_f32 v[194:195], v[142:143], v[14:15], v[194:195]
	v_pk_fma_f32 v[196:197], v[142:143], v[30:31], v[196:197]
	v_pk_fma_f32 v[198:199], v[142:143], v[46:47], v[198:199]
	v_pk_fma_f32 v[200:201], v[142:143], v[62:63], v[200:201]
	v_pk_fma_f32 v[202:203], v[142:143], v[78:79], v[202:203]
	v_pk_fma_f32 v[204:205], v[142:143], v[94:95], v[204:205]
	v_pk_fma_f32 v[206:207], v[142:143], v[110:111], v[206:207]
	v_pk_fma_f32 v[182:183], v[142:143], v[126:127], v[182:183]
	v_pk_fma_f32 v[194:195], v[144:145], v[16:17], v[194:195]
	v_pk_fma_f32 v[196:197], v[144:145], v[32:33], v[196:197]
	v_pk_fma_f32 v[198:199], v[144:145], v[48:49], v[198:199]
	v_pk_fma_f32 v[200:201], v[144:145], v[64:65], v[200:201]
	v_pk_fma_f32 v[202:203], v[144:145], v[80:81], v[202:203]
	v_pk_fma_f32 v[204:205], v[144:145], v[96:97], v[204:205]
	v_pk_fma_f32 v[206:207], v[144:145], v[112:113], v[206:207]
	v_pk_fma_f32 v[182:183], v[144:145], v[128:129], v[182:183]
	v_add_f32_e32 v194, v194, v195
	v_add_f32_e32 v196, v196, v197
	v_add_f32_e32 v198, v198, v199
	v_add_f32_e32 v200, v200, v201
	v_add_f32_e32 v202, v202, v203
	v_add_f32_e32 v204, v204, v205
	v_add_f32_e32 v206, v206, v207
	v_add_f32_e32 v182, v182, v183
	s_nop 1
	v_permlane32_swap_b32_e32 v194, v202
	v_permlane32_swap_b32_e32 v196, v204
	v_permlane32_swap_b32_e32 v198, v206
	v_permlane32_swap_b32_e32 v200, v182
	v_add_f32_e32 v194, v194, v202
	v_add_f32_e32 v196, v196, v204
	v_add_f32_e32 v198, v198, v206
	v_add_f32_e32 v200, v200, v182
	s_nop 1
	v_permlane16_swap_b32_e32 v194, v198
	v_permlane16_swap_b32_e32 v196, v200
	v_add_f32_e32 v194, v194, v198
	v_add_f32_e32 v196, v196, v200
	s_nop 1
	v_add_f32_dpp v235, v194, v194 row_ror:8 row_mask:0xf bank_mask:0x3
	v_add_f32_dpp v235, v196, v196 row_ror:8 row_mask:0xf bank_mask:0xc
	s_waitcnt vmcnt(6)
; __device__ __forceinline__ void fg_tail(const Args& a, int l, LAS unsigned char* lds, const int tid) {
;     ...
;             for (int j = 0; j < 4; ++j) { const int row = rowc + jb + j; rs4v[j] = *(const f32x4*)(rowss + (size_t)row * 4); w0v[j] = *(const u32x4*)(H + (size_t)row * DM + 16 * lane); w1v[j] = *(const u32x4*)(H + (size_t)row * DM + 16 * lane + 8); }
; #pragma unroll
;             for (int j = 0; j < 4; ++j) {
;                 const int row = rowc + jb + j;
;                 const f32x4 rs4 = rs4v[j]; const u32x4 w0 = w0v[j], w1 = w1v[j];
;                 const float r = 1.0f / sqrtf(((rs4[0] + rs4[1]) + (rs4[2] + rs4[3])) * (1.0f / 1024.0f) + EPS);
;                 float h[16];
; #pragma unroll
;                 for (int i = 0; i < 4; ++i) { h[2 * i] = __uint_as_float(w0[i] << 16); h[2 * i + 1] = __uint_as_float(w0[i] & 0xffff0000u); h[8 + 2 * i] = __uint_as_float(w1[i] << 16); h[8 + 2 * i + 1] = __uint_as_float(w1[i] & 0xffff0000u); }
; #pragma unroll
;                 for (int q = 0; q < 4; ++q) { h[4 * q] = h[4 * q] * r + sh[q][0]; h[4 * q + 1] = h[4 * q + 1] * r + sh[q][1]; h[4 * q + 2] = h[4 * q + 2] * r + sh[q][2]; h[4 * q + 3] = h[4 * q + 3] * r + sh[q][3]; }
;                 float d8[8];
; #pragma unroll
;                 for (int j8 = 0; j8 < 8; ++j8) { float acc = 0.f;
; #pragma unroll
;                     for (int q = 0; q < 4; ++q) { const f32x4 w = wl[(j8 * 4 + q) * 64 + lane]; acc += (h[4 * q] * w[0] + h[4 * q + 1] * w[1]) + (h[4 * q + 2] * w[2] + h[4 * q + 3] * w[3]); }
;                     d8[j8] = acc; }
;                 const float tot = reduce8(d8, lane);
	v_lshlrev_b32_e32 v130, 16, v170
	v_and_b32_e32 v131, 0xffff0000, v170
	v_lshlrev_b32_e32 v132, 16, v171
	v_and_b32_e32 v133, 0xffff0000, v171
	v_lshlrev_b32_e32 v134, 16, v172
	v_and_b32_e32 v135, 0xffff0000, v172
	v_lshlrev_b32_e32 v136, 16, v173
	v_and_b32_e32 v137, 0xffff0000, v173
	v_lshlrev_b32_e32 v138, 16, v174
	v_and_b32_e32 v139, 0xffff0000, v174
	v_lshlrev_b32_e32 v140, 16, v175
	v_and_b32_e32 v141, 0xffff0000, v175
	v_lshlrev_b32_e32 v142, 16, v176
	v_and_b32_e32 v143, 0xffff0000, v176
	v_lshlrev_b32_e32 v144, 16, v177
	v_and_b32_e32 v145, 0xffff0000, v177
	global_load_dwordx4 v[170:173], v184, s[94:95] offset:2048
	global_load_dwordx4 v[174:177], v184, s[94:95] offset:2064
	v_pk_mul_f32 v[194:195], v[130:131], v[2:3]
	v_pk_mul_f32 v[196:197], v[130:131], v[18:19]
	v_pk_mul_f32 v[198:199], v[130:131], v[34:35]
	v_pk_mul_f32 v[200:201], v[130:131], v[50:51]
	v_pk_mul_f32 v[202:203], v[130:131], v[66:67]
	v_pk_mul_f32 v[204:205], v[130:131], v[82:83]
	v_pk_mul_f32 v[206:207], v[130:131], v[98:99]
	v_pk_mul_f32 v[182:183], v[130:131], v[114:115]
	v_pk_fma_f32 v[194:195], v[132:133], v[4:5], v[194:195]
	v_pk_fma_f32 v[196:197], v[132:133], v[20:21], v[196:197]
	v_pk_fma_f32 v[198:199], v[132:133], v[36:37], v[198:199]
	v_pk_fma_f32 v[200:201], v[132:133], v[52:53], v[200:201]
	v_pk_fma_f32 v[202:203], v[132:133], v[68:69], v[202:203]
	v_pk_fma_f32 v[204:205], v[132:133], v[84:85], v[204:205]
	v_pk_fma_f32 v[206:207], v[132:133], v[100:101], v[206:207]
	v_pk_fma_f32 v[182:183], v[132:133], v[116:117], v[182:183]
	v_pk_fma_f32 v[194:195], v[134:135], v[6:7], v[194:195]
	v_pk_fma_f32 v[196:197], v[134:135], v[22:23], v[196:197]
	v_pk_fma_f32 v[198:199], v[134:135], v[38:39], v[198:199]
	v_pk_fma_f32 v[200:201], v[134:135], v[54:55], v[200:201]
	v_pk_fma_f32 v[202:203], v[134:135], v[70:71], v[202:203]
	v_pk_fma_f32 v[204:205], v[134:135], v[86:87], v[204:205]
	v_pk_fma_f32 v[206:207], v[134:135], v[102:103], v[206:207]
	v_pk_fma_f32 v[182:183], v[134:135], v[118:119], v[182:183]
	v_pk_fma_f32 v[194:195], v[136:137], v[8:9], v[194:195]
	v_pk_fma_f32 v[196:197], v[136:137], v[24:25], v[196:197]
	v_pk_fma_f32 v[198:199], v[136:137], v[40:41], v[198:199]
	v_pk_fma_f32 v[200:201], v[136:137], v[56:57], v[200:201]
	v_pk_fma_f32 v[202:203], v[136:137], v[72:73], v[202:203]
	v_pk_fma_f32 v[204:205], v[136:137], v[88:89], v[204:205]
	v_pk_fma_f32 v[206:207], v[136:137], v[104:105], v[206:207]
	v_pk_fma_f32 v[182:183], v[136:137], v[120:121], v[182:183]
	v_pk_fma_f32 v[194:195], v[138:139], v[10:11], v[194:195]
	v_pk_fma_f32 v[196:197], v[138:139], v[26:27], v[196:197]
	v_pk_fma_f32 v[198:199], v[138:139], v[42:43], v[198:199]
	v_pk_fma_f32 v[200:201], v[138:139], v[58:59], v[200:201]
	v_pk_fma_f32 v[202:203], v[138:139], v[74:75], v[202:203]
	v_pk_fma_f32 v[204:205], v[138:139], v[90:91], v[204:205]
	v_pk_fma_f32 v[206:207], v[138:139], v[106:107], v[206:207]
	v_pk_fma_f32 v[182:183], v[138:139], v[122:123], v[182:183]
	v_pk_fma_f32 v[194:195], v[140:141], v[12:13], v[194:195]
	v_pk_fma_f32 v[196:197], v[140:141], v[28:29], v[196:197]
	v_pk_fma_f32 v[198:199], v[140:141], v[44:45], v[198:199]
	v_pk_fma_f32 v[200:201], v[140:141], v[60:61], v[200:201]
	v_pk_fma_f32 v[202:203], v[140:141], v[76:77], v[202:203]
	v_pk_fma_f32 v[204:205], v[140:141], v[92:93], v[204:205]
	v_pk_fma_f32 v[206:207], v[140:141], v[108:109], v[206:207]
	v_pk_fma_f32 v[182:183], v[140:141], v[124:125], v[182:183]
	v_pk_fma_f32 v[194:195], v[142:143], v[14:15], v[194:195]
	v_pk_fma_f32 v[196:197], v[142:143], v[30:31], v[196:197]
	v_pk_fma_f32 v[198:199], v[142:143], v[46:47], v[198:199]
	v_pk_fma_f32 v[200:201], v[142:143], v[62:63], v[200:201]
	v_pk_fma_f32 v[202:203], v[142:143], v[78:79], v[202:203]
	v_pk_fma_f32 v[204:205], v[142:143], v[94:95], v[204:205]
	v_pk_fma_f32 v[206:207], v[142:143], v[110:111], v[206:207]
	v_pk_fma_f32 v[182:183], v[142:143], v[126:127], v[182:183]
	v_pk_fma_f32 v[194:195], v[144:145], v[16:17], v[194:195]
	v_pk_fma_f32 v[196:197], v[144:145], v[32:33], v[196:197]
	v_pk_fma_f32 v[198:199], v[144:145], v[48:49], v[198:199]
	v_pk_fma_f32 v[200:201], v[144:145], v[64:65], v[200:201]
	v_pk_fma_f32 v[202:203], v[144:145], v[80:81], v[202:203]
	v_pk_fma_f32 v[204:205], v[144:145], v[96:97], v[204:205]
	v_pk_fma_f32 v[206:207], v[144:145], v[112:113], v[206:207]
	v_pk_fma_f32 v[182:183], v[144:145], v[128:129], v[182:183]
	v_add_f32_e32 v194, v194, v195
	v_add_f32_e32 v196, v196, v197
	v_add_f32_e32 v198, v198, v199
	v_add_f32_e32 v200, v200, v201
	v_add_f32_e32 v202, v202, v203
	v_add_f32_e32 v204, v204, v205
	v_add_f32_e32 v206, v206, v207
	v_add_f32_e32 v182, v182, v183
	s_nop 1
	v_permlane32_swap_b32_e32 v194, v202
	v_permlane32_swap_b32_e32 v196, v204
	v_permlane32_swap_b32_e32 v198, v206
	v_permlane32_swap_b32_e32 v200, v182
	v_add_f32_e32 v194, v194, v202
	v_add_f32_e32 v196, v196, v204
	v_add_f32_e32 v198, v198, v206
	v_add_f32_e32 v200, v200, v182
	s_nop 1
	v_permlane16_swap_b32_e32 v194, v198
	v_permlane16_swap_b32_e32 v196, v200
	v_add_f32_e32 v194, v194, v198
	v_add_f32_e32 v196, v196, v200
	s_nop 1
	v_add_f32_dpp v236, v194, v194 row_ror:8 row_mask:0xf bank_mask:0x3
	v_add_f32_dpp v236, v196, v196 row_ror:8 row_mask:0xf bank_mask:0xc
	s_waitcnt vmcnt(6)
; __device__ __forceinline__ void fg_tail(const Args& a, int l, LAS unsigned char* lds, const int tid) {
;     ...
;             for (int j = 0; j < 4; ++j) { const int row = rowc + jb + j; rs4v[j] = *(const f32x4*)(rowss + (size_t)row * 4); w0v[j] = *(const u32x4*)(H + (size_t)row * DM + 16 * lane); w1v[j] = *(const u32x4*)(H + (size_t)row * DM + 16 * lane + 8); }
; #pragma unroll
;             for (int j = 0; j < 4; ++j) {
;                 const int row = rowc + jb + j;
;                 const f32x4 rs4 = rs4v[j]; const u32x4 w0 = w0v[j], w1 = w1v[j];
;                 const float r = 1.0f / sqrtf(((rs4[0] + rs4[1]) + (rs4[2] + rs4[3])) * (1.0f / 1024.0f) + EPS);
;                 float h[16];
; #pragma unroll
;                 for (int i = 0; i < 4; ++i) { h[2 * i] = __uint_as_float(w0[i] << 16); h[2 * i + 1] = __uint_as_float(w0[i] & 0xffff0000u); h[8 + 2 * i] = __uint_as_float(w1[i] << 16); h[8 + 2 * i + 1] = __uint_as_float(w1[i] & 0xffff0000u); }
; #pragma unroll
;                 for (int q = 0; q < 4; ++q) { h[4 * q] = h[4 * q] * r + sh[q][0]; h[4 * q + 1] = h[4 * q + 1] * r + sh[q][1]; h[4 * q + 2] = h[4 * q + 2] * r + sh[q][2]; h[4 * q + 3] = h[4 * q + 3] * r + sh[q][3]; }
;                 float d8[8];
; #pragma unroll
;                 for (int j8 = 0; j8 < 8; ++j8) { float acc = 0.f;
; #pragma unroll
;                     for (int q = 0; q < 4; ++q) { const f32x4 w = wl[(j8 * 4 + q) * 64 + lane]; acc += (h[4 * q] * w[0] + h[4 * q + 1] * w[1]) + (h[4 * q + 2] * w[2] + h[4 * q + 3] * w[3]); }
;                     d8[j8] = acc; }
;                 const float tot = reduce8(d8, lane);
	v_lshlrev_b32_e32 v130, 16, v146
	v_and_b32_e32 v131, 0xffff0000, v146
	v_lshlrev_b32_e32 v132, 16, v147
	v_and_b32_e32 v133, 0xffff0000, v147
	v_lshlrev_b32_e32 v134, 16, v148
	v_and_b32_e32 v135, 0xffff0000, v148
	v_lshlrev_b32_e32 v136, 16, v149
	v_and_b32_e32 v137, 0xffff0000, v149
	v_lshlrev_b32_e32 v138, 16, v150
	v_and_b32_e32 v139, 0xffff0000, v150
	v_lshlrev_b32_e32 v140, 16, v151
	v_and_b32_e32 v141, 0xffff0000, v151
	v_lshlrev_b32_e32 v142, 16, v152
	v_and_b32_e32 v143, 0xffff0000, v152
	v_lshlrev_b32_e32 v144, 16, v153
	v_and_b32_e32 v145, 0xffff0000, v153
	v_pk_mul_f32 v[194:195], v[130:131], v[2:3]
	v_pk_mul_f32 v[196:197], v[130:131], v[18:19]
	v_pk_mul_f32 v[198:199], v[130:131], v[34:35]
	v_pk_mul_f32 v[200:201], v[130:131], v[50:51]
	v_pk_mul_f32 v[202:203], v[130:131], v[66:67]
	v_pk_mul_f32 v[204:205], v[130:131], v[82:83]
	v_pk_mul_f32 v[206:207], v[130:131], v[98:99]
	v_pk_mul_f32 v[182:183], v[130:131], v[114:115]
	v_pk_fma_f32 v[194:195], v[132:133], v[4:5], v[194:195]
	v_pk_fma_f32 v[196:197], v[132:133], v[20:21], v[196:197]
	v_pk_fma_f32 v[198:199], v[132:133], v[36:37], v[198:199]
	v_pk_fma_f32 v[200:201], v[132:133], v[52:53], v[200:201]
	v_pk_fma_f32 v[202:203], v[132:133], v[68:69], v[202:203]
	v_pk_fma_f32 v[204:205], v[132:133], v[84:85], v[204:205]
	v_pk_fma_f32 v[206:207], v[132:133], v[100:101], v[206:207]
	v_pk_fma_f32 v[182:183], v[132:133], v[116:117], v[182:183]
	v_pk_fma_f32 v[194:195], v[134:135], v[6:7], v[194:195]
	v_pk_fma_f32 v[196:197], v[134:135], v[22:23], v[196:197]
	v_pk_fma_f32 v[198:199], v[134:135], v[38:39], v[198:199]
	v_pk_fma_f32 v[200:201], v[134:135], v[54:55], v[200:201]
	v_pk_fma_f32 v[202:203], v[134:135], v[70:71], v[202:203]
	v_pk_fma_f32 v[204:205], v[134:135], v[86:87], v[204:205]
	v_pk_fma_f32 v[206:207], v[134:135], v[102:103], v[206:207]
	v_pk_fma_f32 v[182:183], v[134:135], v[118:119], v[182:183]
	v_pk_fma_f32 v[194:195], v[136:137], v[8:9], v[194:195]
	v_pk_fma_f32 v[196:197], v[136:137], v[24:25], v[196:197]
	v_pk_fma_f32 v[198:199], v[136:137], v[40:41], v[198:199]
	v_pk_fma_f32 v[200:201], v[136:137], v[56:57], v[200:201]
	v_pk_fma_f32 v[202:203], v[136:137], v[72:73], v[202:203]
	v_pk_fma_f32 v[204:205], v[136:137], v[88:89], v[204:205]
	v_pk_fma_f32 v[206:207], v[136:137], v[104:105], v[206:207]
	v_pk_fma_f32 v[182:183], v[136:137], v[120:121], v[182:183]
	v_pk_fma_f32 v[194:195], v[138:139], v[10:11], v[194:195]
	v_pk_fma_f32 v[196:197], v[138:139], v[26:27], v[196:197]
	v_pk_fma_f32 v[198:199], v[138:139], v[42:43], v[198:199]
	v_pk_fma_f32 v[200:201], v[138:139], v[58:59], v[200:201]
	v_pk_fma_f32 v[202:203], v[138:139], v[74:75], v[202:203]
	v_pk_fma_f32 v[204:205], v[138:139], v[90:91], v[204:205]
	v_pk_fma_f32 v[206:207], v[138:139], v[106:107], v[206:207]
	v_pk_fma_f32 v[182:183], v[138:139], v[122:123], v[182:183]
	v_pk_fma_f32 v[194:195], v[140:141], v[12:13], v[194:195]
	v_pk_fma_f32 v[196:197], v[140:141], v[28:29], v[196:197]
	v_pk_fma_f32 v[198:199], v[140:141], v[44:45], v[198:199]
	v_pk_fma_f32 v[200:201], v[140:141], v[60:61], v[200:201]
	v_pk_fma_f32 v[202:203], v[140:141], v[76:77], v[202:203]
	v_pk_fma_f32 v[204:205], v[140:141], v[92:93], v[204:205]
	v_pk_fma_f32 v[206:207], v[140:141], v[108:109], v[206:207]
	v_pk_fma_f32 v[182:183], v[140:141], v[124:125], v[182:183]
	v_pk_fma_f32 v[194:195], v[142:143], v[14:15], v[194:195]
	v_pk_fma_f32 v[196:197], v[142:143], v[30:31], v[196:197]
	v_pk_fma_f32 v[198:199], v[142:143], v[46:47], v[198:199]
	v_pk_fma_f32 v[200:201], v[142:143], v[62:63], v[200:201]
	v_pk_fma_f32 v[202:203], v[142:143], v[78:79], v[202:203]
	v_pk_fma_f32 v[204:205], v[142:143], v[94:95], v[204:205]
	v_pk_fma_f32 v[206:207], v[142:143], v[110:111], v[206:207]
	v_pk_fma_f32 v[182:183], v[142:143], v[126:127], v[182:183]
	v_pk_fma_f32 v[194:195], v[144:145], v[16:17], v[194:195]
	v_pk_fma_f32 v[196:197], v[144:145], v[32:33], v[196:197]
	v_pk_fma_f32 v[198:199], v[144:145], v[48:49], v[198:199]
	v_pk_fma_f32 v[200:201], v[144:145], v[64:65], v[200:201]
	v_pk_fma_f32 v[202:203], v[144:145], v[80:81], v[202:203]
	v_pk_fma_f32 v[204:205], v[144:145], v[96:97], v[204:205]
	v_pk_fma_f32 v[206:207], v[144:145], v[112:113], v[206:207]
	v_pk_fma_f32 v[182:183], v[144:145], v[128:129], v[182:183]
	v_add_f32_e32 v194, v194, v195
	v_add_f32_e32 v196, v196, v197
	v_add_f32_e32 v198, v198, v199
	v_add_f32_e32 v200, v200, v201
	v_add_f32_e32 v202, v202, v203
	v_add_f32_e32 v204, v204, v205
	v_add_f32_e32 v206, v206, v207
	v_add_f32_e32 v182, v182, v183
	s_nop 1
	v_permlane32_swap_b32_e32 v194, v202
	v_permlane32_swap_b32_e32 v196, v204
	v_permlane32_swap_b32_e32 v198, v206
	v_permlane32_swap_b32_e32 v200, v182
	v_add_f32_e32 v194, v194, v202
	v_add_f32_e32 v196, v196, v204
	v_add_f32_e32 v198, v198, v206
	v_add_f32_e32 v200, v200, v182
	s_nop 1
	v_permlane16_swap_b32_e32 v194, v198
	v_permlane16_swap_b32_e32 v196, v200
	v_add_f32_e32 v194, v194, v198
	v_add_f32_e32 v196, v196, v200
	s_nop 1
	v_add_f32_dpp v237, v194, v194 row_ror:8 row_mask:0xf bank_mask:0x3
	v_add_f32_dpp v237, v196, v196 row_ror:8 row_mask:0xf bank_mask:0xc
	s_waitcnt vmcnt(4)
; __device__ __forceinline__ void fg_tail(const Args& a, int l, LAS unsigned char* lds, const int tid) {
;     ...
;             for (int j = 0; j < 4; ++j) { const int row = rowc + jb + j; rs4v[j] = *(const f32x4*)(rowss + (size_t)row * 4); w0v[j] = *(const u32x4*)(H + (size_t)row * DM + 16 * lane); w1v[j] = *(const u32x4*)(H + (size_t)row * DM + 16 * lane + 8); }
; #pragma unroll
;             for (int j = 0; j < 4; ++j) {
;                 const int row = rowc + jb + j;
;                 const f32x4 rs4 = rs4v[j]; const u32x4 w0 = w0v[j], w1 = w1v[j];
;                 const float r = 1.0f / sqrtf(((rs4[0] + rs4[1]) + (rs4[2] + rs4[3])) * (1.0f / 1024.0f) + EPS);
;                 float h[16];
; #pragma unroll
;                 for (int i = 0; i < 4; ++i) { h[2 * i] = __uint_as_float(w0[i] << 16); h[2 * i + 1] = __uint_as_float(w0[i] & 0xffff0000u); h[8 + 2 * i] = __uint_as_float(w1[i] << 16); h[8 + 2 * i + 1] = __uint_as_float(w1[i] & 0xffff0000u); }
; #pragma unroll
;                 for (int q = 0; q < 4; ++q) { h[4 * q] = h[4 * q] * r + sh[q][0]; h[4 * q + 1] = h[4 * q + 1] * r + sh[q][1]; h[4 * q + 2] = h[4 * q + 2] * r + sh[q][2]; h[4 * q + 3] = h[4 * q + 3] * r + sh[q][3]; }
;                 float d8[8];
; #pragma unroll
;                 for (int j8 = 0; j8 < 8; ++j8) { float acc = 0.f;
; #pragma unroll
;                     for (int q = 0; q < 4; ++q) { const f32x4 w = wl[(j8 * 4 + q) * 64 + lane]; acc += (h[4 * q] * w[0] + h[4 * q + 1] * w[1]) + (h[4 * q + 2] * w[2] + h[4 * q + 3] * w[3]); }
;                     d8[j8] = acc; }
;                 const float tot = reduce8(d8, lane);
	v_lshlrev_b32_e32 v130, 16, v154
	v_and_b32_e32 v131, 0xffff0000, v154
	v_lshlrev_b32_e32 v132, 16, v155
	v_and_b32_e32 v133, 0xffff0000, v155
	v_lshlrev_b32_e32 v134, 16, v156
	v_and_b32_e32 v135, 0xffff0000, v156
	v_lshlrev_b32_e32 v136, 16, v157
	v_and_b32_e32 v137, 0xffff0000, v157
	v_lshlrev_b32_e32 v138, 16, v158
	v_and_b32_e32 v139, 0xffff0000, v158
	v_lshlrev_b32_e32 v140, 16, v159
	v_and_b32_e32 v141, 0xffff0000, v159
	v_lshlrev_b32_e32 v142, 16, v160
	v_and_b32_e32 v143, 0xffff0000, v160
	v_lshlrev_b32_e32 v144, 16, v161
	v_and_b32_e32 v145, 0xffff0000, v161
	v_pk_mul_f32 v[194:195], v[130:131], v[2:3]
	v_pk_mul_f32 v[196:197], v[130:131], v[18:19]
	v_pk_mul_f32 v[198:199], v[130:131], v[34:35]
	v_pk_mul_f32 v[200:201], v[130:131], v[50:51]
	v_pk_mul_f32 v[202:203], v[130:131], v[66:67]
	v_pk_mul_f32 v[204:205], v[130:131], v[82:83]
	v_pk_mul_f32 v[206:207], v[130:131], v[98:99]
	v_pk_mul_f32 v[182:183], v[130:131], v[114:115]
	v_pk_fma_f32 v[194:195], v[132:133], v[4:5], v[194:195]
	v_pk_fma_f32 v[196:197], v[132:133], v[20:21], v[196:197]
	v_pk_fma_f32 v[198:199], v[132:133], v[36:37], v[198:199]
	v_pk_fma_f32 v[200:201], v[132:133], v[52:53], v[200:201]
	v_pk_fma_f32 v[202:203], v[132:133], v[68:69], v[202:203]
	v_pk_fma_f32 v[204:205], v[132:133], v[84:85], v[204:205]
	v_pk_fma_f32 v[206:207], v[132:133], v[100:101], v[206:207]
	v_pk_fma_f32 v[182:183], v[132:133], v[116:117], v[182:183]
	v_pk_fma_f32 v[194:195], v[134:135], v[6:7], v[194:195]
	v_pk_fma_f32 v[196:197], v[134:135], v[22:23], v[196:197]
	v_pk_fma_f32 v[198:199], v[134:135], v[38:39], v[198:199]
	v_pk_fma_f32 v[200:201], v[134:135], v[54:55], v[200:201]
	v_pk_fma_f32 v[202:203], v[134:135], v[70:71], v[202:203]
	v_pk_fma_f32 v[204:205], v[134:135], v[86:87], v[204:205]
	v_pk_fma_f32 v[206:207], v[134:135], v[102:103], v[206:207]
	v_pk_fma_f32 v[182:183], v[134:135], v[118:119], v[182:183]
	v_pk_fma_f32 v[194:195], v[136:137], v[8:9], v[194:195]
	v_pk_fma_f32 v[196:197], v[136:137], v[24:25], v[196:197]
	v_pk_fma_f32 v[198:199], v[136:137], v[40:41], v[198:199]
	v_pk_fma_f32 v[200:201], v[136:137], v[56:57], v[200:201]
	v_pk_fma_f32 v[202:203], v[136:137], v[72:73], v[202:203]
	v_pk_fma_f32 v[204:205], v[136:137], v[88:89], v[204:205]
	v_pk_fma_f32 v[206:207], v[136:137], v[104:105], v[206:207]
	v_pk_fma_f32 v[182:183], v[136:137], v[120:121], v[182:183]
	v_pk_fma_f32 v[194:195], v[138:139], v[10:11], v[194:195]
	v_pk_fma_f32 v[196:197], v[138:139], v[26:27], v[196:197]
	v_pk_fma_f32 v[198:199], v[138:139], v[42:43], v[198:199]
	v_pk_fma_f32 v[200:201], v[138:139], v[58:59], v[200:201]
	v_pk_fma_f32 v[202:203], v[138:139], v[74:75], v[202:203]
	v_pk_fma_f32 v[204:205], v[138:139], v[90:91], v[204:205]
	v_pk_fma_f32 v[206:207], v[138:139], v[106:107], v[206:207]
	v_pk_fma_f32 v[182:183], v[138:139], v[122:123], v[182:183]
	v_pk_fma_f32 v[194:195], v[140:141], v[12:13], v[194:195]
	v_pk_fma_f32 v[196:197], v[140:141], v[28:29], v[196:197]
	v_pk_fma_f32 v[198:199], v[140:141], v[44:45], v[198:199]
	v_pk_fma_f32 v[200:201], v[140:141], v[60:61], v[200:201]
	v_pk_fma_f32 v[202:203], v[140:141], v[76:77], v[202:203]
	v_pk_fma_f32 v[204:205], v[140:141], v[92:93], v[204:205]
	v_pk_fma_f32 v[206:207], v[140:141], v[108:109], v[206:207]
	v_pk_fma_f32 v[182:183], v[140:141], v[124:125], v[182:183]
	v_pk_fma_f32 v[194:195], v[142:143], v[14:15], v[194:195]
	v_pk_fma_f32 v[196:197], v[142:143], v[30:31], v[196:197]
	v_pk_fma_f32 v[198:199], v[142:143], v[46:47], v[198:199]
	v_pk_fma_f32 v[200:201], v[142:143], v[62:63], v[200:201]
	v_pk_fma_f32 v[202:203], v[142:143], v[78:79], v[202:203]
	v_pk_fma_f32 v[204:205], v[142:143], v[94:95], v[204:205]
	v_pk_fma_f32 v[206:207], v[142:143], v[110:111], v[206:207]
	v_pk_fma_f32 v[182:183], v[142:143], v[126:127], v[182:183]
	v_pk_fma_f32 v[194:195], v[144:145], v[16:17], v[194:195]
	v_pk_fma_f32 v[196:197], v[144:145], v[32:33], v[196:197]
	v_pk_fma_f32 v[198:199], v[144:145], v[48:49], v[198:199]
	v_pk_fma_f32 v[200:201], v[144:145], v[64:65], v[200:201]
	v_pk_fma_f32 v[202:203], v[144:145], v[80:81], v[202:203]
	v_pk_fma_f32 v[204:205], v[144:145], v[96:97], v[204:205]
	v_pk_fma_f32 v[206:207], v[144:145], v[112:113], v[206:207]
	v_pk_fma_f32 v[182:183], v[144:145], v[128:129], v[182:183]
	v_add_f32_e32 v194, v194, v195
	v_add_f32_e32 v196, v196, v197
	v_add_f32_e32 v198, v198, v199
	v_add_f32_e32 v200, v200, v201
	v_add_f32_e32 v202, v202, v203
	v_add_f32_e32 v204, v204, v205
	v_add_f32_e32 v206, v206, v207
	v_add_f32_e32 v182, v182, v183
	s_nop 1
	v_permlane32_swap_b32_e32 v194, v202
	v_permlane32_swap_b32_e32 v196, v204
	v_permlane32_swap_b32_e32 v198, v206
	v_permlane32_swap_b32_e32 v200, v182
	v_add_f32_e32 v194, v194, v202
	v_add_f32_e32 v196, v196, v204
	v_add_f32_e32 v198, v198, v206
	v_add_f32_e32 v200, v200, v182
	s_nop 1
	v_permlane16_swap_b32_e32 v194, v198
	v_permlane16_swap_b32_e32 v196, v200
	v_add_f32_e32 v194, v194, v198
	v_add_f32_e32 v196, v196, v200
	s_nop 1
	v_add_f32_dpp v238, v194, v194 row_ror:8 row_mask:0xf bank_mask:0x3
	v_add_f32_dpp v238, v196, v196 row_ror:8 row_mask:0xf bank_mask:0xc
	s_waitcnt vmcnt(2)
; __device__ __forceinline__ float reduce8(const float (&d)[8], int lane) {
;     ...
;     for (int i = 0; i < 4; ++i) { const float snd = h32 ? d[i] : d[4 + i], kp = h32 ? d[4 + i] : d[i]; e[i] = kp + __shfl_xor(snd, 32); }
;     float f[2];
; #pragma unroll
;     for (int i = 0; i < 2; ++i) { const float snd = h16 ? e[i] : e[2 + i], kp = h16 ? e[2 + i] : e[i]; f[i] = kp + __shfl_xor(snd, 16); }
;     const float snd = h8 ? f[0] : f[1], kp = h8 ? f[1] : f[0];
;     float g = kp + __shfl_xor(snd, 8);
; __device__ __forceinline__ void fg_tail(const Args& a, int l, LAS unsigned char* lds, const int tid) {
;     ...
;                 float h[16];
; #pragma unroll
;                 for (int i = 0; i < 4; ++i) { h[2 * i] = __uint_as_float(w0[i] << 16); h[2 * i + 1] = __uint_as_float(w0[i] & 0xffff0000u); h[8 + 2 * i] = __uint_as_float(w1[i] << 16); h[8 + 2 * i + 1] = __uint_as_float(w1[i] & 0xffff0000u); }
; #pragma unroll
;                 for (int q = 0; q < 4; ++q) { h[4 * q] = h[4 * q] * r + sh[q][0]; h[4 * q + 1] = h[4 * q + 1] * r + sh[q][1]; h[4 * q + 2] = h[4 * q + 2] * r + sh[q][2]; h[4 * q + 3] = h[4 * q + 3] * r + sh[q][3]; }
;                 float d8[8];
; #pragma unroll
;                 for (int j8 = 0; j8 < 8; ++j8) { float acc = 0.f;
; #pragma unroll
;                     for (int q = 0; q < 4; ++q) { const f32x4 w = wl[(j8 * 4 + q) * 64 + lane]; acc += (h[4 * q] * w[0] + h[4 * q + 1] * w[1]) + (h[4 * q + 2] * w[2] + h[4 * q + 3] * w[3]); }
;                     d8[j8] = acc; }
	v_lshlrev_b32_e32 v130, 16, v162
	v_and_b32_e32 v131, 0xffff0000, v162
	v_lshlrev_b32_e32 v132, 16, v163
	v_and_b32_e32 v133, 0xffff0000, v163
	v_lshlrev_b32_e32 v134, 16, v164
	v_and_b32_e32 v135, 0xffff0000, v164
	v_lshlrev_b32_e32 v136, 16, v165
	v_and_b32_e32 v137, 0xffff0000, v165
	v_lshlrev_b32_e32 v138, 16, v166
	v_and_b32_e32 v139, 0xffff0000, v166
	v_lshlrev_b32_e32 v140, 16, v167
	v_and_b32_e32 v141, 0xffff0000, v167
	v_lshlrev_b32_e32 v142, 16, v168
	v_and_b32_e32 v143, 0xffff0000, v168
	v_lshlrev_b32_e32 v144, 16, v169
	v_and_b32_e32 v145, 0xffff0000, v169
	v_pk_mul_f32 v[194:195], v[130:131], v[2:3]
	v_pk_mul_f32 v[196:197], v[130:131], v[18:19]
	v_pk_mul_f32 v[198:199], v[130:131], v[34:35]
	v_pk_mul_f32 v[200:201], v[130:131], v[50:51]
	v_pk_mul_f32 v[202:203], v[130:131], v[66:67]
	v_pk_mul_f32 v[204:205], v[130:131], v[82:83]
	v_pk_mul_f32 v[206:207], v[130:131], v[98:99]
	v_pk_mul_f32 v[182:183], v[130:131], v[114:115]
	v_pk_fma_f32 v[194:195], v[132:133], v[4:5], v[194:195]
	v_pk_fma_f32 v[196:197], v[132:133], v[20:21], v[196:197]
	v_pk_fma_f32 v[198:199], v[132:133], v[36:37], v[198:199]
	v_pk_fma_f32 v[200:201], v[132:133], v[52:53], v[200:201]
	v_pk_fma_f32 v[202:203], v[132:133], v[68:69], v[202:203]
	v_pk_fma_f32 v[204:205], v[132:133], v[84:85], v[204:205]
	v_pk_fma_f32 v[206:207], v[132:133], v[100:101], v[206:207]
	v_pk_fma_f32 v[182:183], v[132:133], v[116:117], v[182:183]
	v_pk_fma_f32 v[194:195], v[134:135], v[6:7], v[194:195]
	v_pk_fma_f32 v[196:197], v[134:135], v[22:23], v[196:197]
	v_pk_fma_f32 v[198:199], v[134:135], v[38:39], v[198:199]
	v_pk_fma_f32 v[200:201], v[134:135], v[54:55], v[200:201]
	v_pk_fma_f32 v[202:203], v[134:135], v[70:71], v[202:203]
	v_pk_fma_f32 v[204:205], v[134:135], v[86:87], v[204:205]
	v_pk_fma_f32 v[206:207], v[134:135], v[102:103], v[206:207]
	v_pk_fma_f32 v[182:183], v[134:135], v[118:119], v[182:183]
	v_pk_fma_f32 v[194:195], v[136:137], v[8:9], v[194:195]
	v_pk_fma_f32 v[196:197], v[136:137], v[24:25], v[196:197]
	v_pk_fma_f32 v[198:199], v[136:137], v[40:41], v[198:199]
	v_pk_fma_f32 v[200:201], v[136:137], v[56:57], v[200:201]
	v_pk_fma_f32 v[202:203], v[136:137], v[72:73], v[202:203]
	v_pk_fma_f32 v[204:205], v[136:137], v[88:89], v[204:205]
	v_pk_fma_f32 v[206:207], v[136:137], v[104:105], v[206:207]
	v_pk_fma_f32 v[182:183], v[136:137], v[120:121], v[182:183]
	v_pk_fma_f32 v[194:195], v[138:139], v[10:11], v[194:195]
	v_pk_fma_f32 v[196:197], v[138:139], v[26:27], v[196:197]
	v_pk_fma_f32 v[198:199], v[138:139], v[42:43], v[198:199]
	v_pk_fma_f32 v[200:201], v[138:139], v[58:59], v[200:201]
	v_pk_fma_f32 v[202:203], v[138:139], v[74:75], v[202:203]
	v_pk_fma_f32 v[204:205], v[138:139], v[90:91], v[204:205]
	v_pk_fma_f32 v[206:207], v[138:139], v[106:107], v[206:207]
	v_pk_fma_f32 v[182:183], v[138:139], v[122:123], v[182:183]
	v_pk_fma_f32 v[194:195], v[140:141], v[12:13], v[194:195]
	v_pk_fma_f32 v[196:197], v[140:141], v[28:29], v[196:197]
	v_pk_fma_f32 v[198:199], v[140:141], v[44:45], v[198:199]
	v_pk_fma_f32 v[200:201], v[140:141], v[60:61], v[200:201]
	v_pk_fma_f32 v[202:203], v[140:141], v[76:77], v[202:203]
	v_pk_fma_f32 v[204:205], v[140:141], v[92:93], v[204:205]
	v_pk_fma_f32 v[206:207], v[140:141], v[108:109], v[206:207]
	v_pk_fma_f32 v[182:183], v[140:141], v[124:125], v[182:183]
	v_pk_fma_f32 v[194:195], v[142:143], v[14:15], v[194:195]
	v_pk_fma_f32 v[196:197], v[142:143], v[30:31], v[196:197]
	v_pk_fma_f32 v[198:199], v[142:143], v[46:47], v[198:199]
	v_pk_fma_f32 v[200:201], v[142:143], v[62:63], v[200:201]
	v_pk_fma_f32 v[202:203], v[142:143], v[78:79], v[202:203]
	v_pk_fma_f32 v[204:205], v[142:143], v[94:95], v[204:205]
	v_pk_fma_f32 v[206:207], v[142:143], v[110:111], v[206:207]
	v_pk_fma_f32 v[182:183], v[142:143], v[126:127], v[182:183]
	v_pk_fma_f32 v[194:195], v[144:145], v[16:17], v[194:195]
	v_pk_fma_f32 v[196:197], v[144:145], v[32:33], v[196:197]
	v_pk_fma_f32 v[198:199], v[144:145], v[48:49], v[198:199]
	v_pk_fma_f32 v[200:201], v[144:145], v[64:65], v[200:201]
	v_pk_fma_f32 v[202:203], v[144:145], v[80:81], v[202:203]
	v_pk_fma_f32 v[204:205], v[144:145], v[96:97], v[204:205]
	v_pk_fma_f32 v[206:207], v[144:145], v[112:113], v[206:207]
	v_pk_fma_f32 v[182:183], v[144:145], v[128:129], v[182:183]
	v_add_f32_e32 v194, v194, v195
	v_add_f32_e32 v196, v196, v197
	v_add_f32_e32 v198, v198, v199
	v_add_f32_e32 v200, v200, v201
	v_add_f32_e32 v202, v202, v203
	v_add_f32_e32 v204, v204, v205
	v_add_f32_e32 v206, v206, v207
	v_add_f32_e32 v182, v182, v183
	s_nop 1
	v_permlane32_swap_b32_e32 v194, v202
	v_permlane32_swap_b32_e32 v196, v204
	v_permlane32_swap_b32_e32 v198, v206
	v_permlane32_swap_b32_e32 v200, v182
	v_add_f32_e32 v194, v194, v202
	v_add_f32_e32 v196, v196, v204
	v_add_f32_e32 v198, v198, v206
	v_add_f32_e32 v200, v200, v182
	s_nop 1
	v_permlane16_swap_b32_e32 v194, v198
	v_permlane16_swap_b32_e32 v196, v200
	v_add_f32_e32 v194, v194, v198
	v_add_f32_e32 v196, v196, v200
	s_nop 1
	v_add_f32_dpp v239, v194, v194 row_ror:8 row_mask:0xf bank_mask:0x3
	v_add_f32_dpp v239, v196, v196 row_ror:8 row_mask:0xf bank_mask:0xc
	s_waitcnt vmcnt(0)
; __device__ __forceinline__ float reduce8(const float (&d)[8], int lane) {
;     ...
;     for (int i = 0; i < 4; ++i) { const float snd = h32 ? d[i] : d[4 + i], kp = h32 ? d[4 + i] : d[i]; e[i] = kp + __shfl_xor(snd, 32); }
;     float f[2];
; #pragma unroll
;     for (int i = 0; i < 2; ++i) { const float snd = h16 ? e[i] : e[2 + i], kp = h16 ? e[2 + i] : e[i]; f[i] = kp + __shfl_xor(snd, 16); }
;     const float snd = h8 ? f[0] : f[1], kp = h8 ? f[1] : f[0];
;     float g = kp + __shfl_xor(snd, 8);
; __device__ __forceinline__ void fg_tail(const Args& a, int l, LAS unsigned char* lds, const int tid) {
;     ...
;                 float h[16];
; #pragma unroll
;                 for (int i = 0; i < 4; ++i) { h[2 * i] = __uint_as_float(w0[i] << 16); h[2 * i + 1] = __uint_as_float(w0[i] & 0xffff0000u); h[8 + 2 * i] = __uint_as_float(w1[i] << 16); h[8 + 2 * i + 1] = __uint_as_float(w1[i] & 0xffff0000u); }
; #pragma unroll
;                 for (int q = 0; q < 4; ++q) { h[4 * q] = h[4 * q] * r + sh[q][0]; h[4 * q + 1] = h[4 * q + 1] * r + sh[q][1]; h[4 * q + 2] = h[4 * q + 2] * r + sh[q][2]; h[4 * q + 3] = h[4 * q + 3] * r + sh[q][3]; }
;                 float d8[8];
; #pragma unroll
;                 for (int j8 = 0; j8 < 8; ++j8) { float acc = 0.f;
; #pragma unroll
;                     for (int q = 0; q < 4; ++q) { const f32x4 w = wl[(j8 * 4 + q) * 64 + lane]; acc += (h[4 * q] * w[0] + h[4 * q + 1] * w[1]) + (h[4 * q + 2] * w[2] + h[4 * q + 3] * w[3]); }
;                     d8[j8] = acc; }
	v_lshlrev_b32_e32 v130, 16, v170
	v_and_b32_e32 v131, 0xffff0000, v170
	v_lshlrev_b32_e32 v132, 16, v171
	v_and_b32_e32 v133, 0xffff0000, v171
	v_lshlrev_b32_e32 v134, 16, v172
	v_and_b32_e32 v135, 0xffff0000, v172
	v_lshlrev_b32_e32 v136, 16, v173
	v_and_b32_e32 v137, 0xffff0000, v173
	v_lshlrev_b32_e32 v138, 16, v174
	v_and_b32_e32 v139, 0xffff0000, v174
	v_lshlrev_b32_e32 v140, 16, v175
	v_and_b32_e32 v141, 0xffff0000, v175
	v_lshlrev_b32_e32 v142, 16, v176
	v_and_b32_e32 v143, 0xffff0000, v176
	v_lshlrev_b32_e32 v144, 16, v177
	v_and_b32_e32 v145, 0xffff0000, v177
	v_pk_mul_f32 v[194:195], v[130:131], v[2:3]
	v_pk_mul_f32 v[196:197], v[130:131], v[18:19]
	v_pk_mul_f32 v[198:199], v[130:131], v[34:35]
	v_pk_mul_f32 v[200:201], v[130:131], v[50:51]
	v_pk_mul_f32 v[202:203], v[130:131], v[66:67]
	v_pk_mul_f32 v[204:205], v[130:131], v[82:83]
	v_pk_mul_f32 v[206:207], v[130:131], v[98:99]
	v_pk_mul_f32 v[182:183], v[130:131], v[114:115]
	v_pk_fma_f32 v[194:195], v[132:133], v[4:5], v[194:195]
	v_pk_fma_f32 v[196:197], v[132:133], v[20:21], v[196:197]
	v_pk_fma_f32 v[198:199], v[132:133], v[36:37], v[198:199]
	v_pk_fma_f32 v[200:201], v[132:133], v[52:53], v[200:201]
	v_pk_fma_f32 v[202:203], v[132:133], v[68:69], v[202:203]
	v_pk_fma_f32 v[204:205], v[132:133], v[84:85], v[204:205]
	v_pk_fma_f32 v[206:207], v[132:133], v[100:101], v[206:207]
	v_pk_fma_f32 v[182:183], v[132:133], v[116:117], v[182:183]
	v_pk_fma_f32 v[194:195], v[134:135], v[6:7], v[194:195]
	v_pk_fma_f32 v[196:197], v[134:135], v[22:23], v[196:197]
	v_pk_fma_f32 v[198:199], v[134:135], v[38:39], v[198:199]
	v_pk_fma_f32 v[200:201], v[134:135], v[54:55], v[200:201]
	v_pk_fma_f32 v[202:203], v[134:135], v[70:71], v[202:203]
	v_pk_fma_f32 v[204:205], v[134:135], v[86:87], v[204:205]
	v_pk_fma_f32 v[206:207], v[134:135], v[102:103], v[206:207]
	v_pk_fma_f32 v[182:183], v[134:135], v[118:119], v[182:183]
	v_pk_fma_f32 v[194:195], v[136:137], v[8:9], v[194:195]
	v_pk_fma_f32 v[196:197], v[136:137], v[24:25], v[196:197]
	v_pk_fma_f32 v[198:199], v[136:137], v[40:41], v[198:199]
	v_pk_fma_f32 v[200:201], v[136:137], v[56:57], v[200:201]
	v_pk_fma_f32 v[202:203], v[136:137], v[72:73], v[202:203]
	v_pk_fma_f32 v[204:205], v[136:137], v[88:89], v[204:205]
	v_pk_fma_f32 v[206:207], v[136:137], v[104:105], v[206:207]
	v_pk_fma_f32 v[182:183], v[136:137], v[120:121], v[182:183]
	v_pk_fma_f32 v[194:195], v[138:139], v[10:11], v[194:195]
	v_pk_fma_f32 v[196:197], v[138:139], v[26:27], v[196:197]
	v_pk_fma_f32 v[198:199], v[138:139], v[42:43], v[198:199]
	v_pk_fma_f32 v[200:201], v[138:139], v[58:59], v[200:201]
	v_pk_fma_f32 v[202:203], v[138:139], v[74:75], v[202:203]
	v_pk_fma_f32 v[204:205], v[138:139], v[90:91], v[204:205]
	v_pk_fma_f32 v[206:207], v[138:139], v[106:107], v[206:207]
	v_pk_fma_f32 v[182:183], v[138:139], v[122:123], v[182:183]
	v_pk_fma_f32 v[194:195], v[140:141], v[12:13], v[194:195]
	v_pk_fma_f32 v[196:197], v[140:141], v[28:29], v[196:197]
	v_pk_fma_f32 v[198:199], v[140:141], v[44:45], v[198:199]
	v_pk_fma_f32 v[200:201], v[140:141], v[60:61], v[200:201]
	v_pk_fma_f32 v[202:203], v[140:141], v[76:77], v[202:203]
	v_pk_fma_f32 v[204:205], v[140:141], v[92:93], v[204:205]
	v_pk_fma_f32 v[206:207], v[140:141], v[108:109], v[206:207]
	v_pk_fma_f32 v[182:183], v[140:141], v[124:125], v[182:183]
	v_pk_fma_f32 v[194:195], v[142:143], v[14:15], v[194:195]
	v_pk_fma_f32 v[196:197], v[142:143], v[30:31], v[196:197]
	v_pk_fma_f32 v[198:199], v[142:143], v[46:47], v[198:199]
	v_pk_fma_f32 v[200:201], v[142:143], v[62:63], v[200:201]
	v_pk_fma_f32 v[202:203], v[142:143], v[78:79], v[202:203]
	v_pk_fma_f32 v[204:205], v[142:143], v[94:95], v[204:205]
	v_pk_fma_f32 v[206:207], v[142:143], v[110:111], v[206:207]
	v_pk_fma_f32 v[182:183], v[142:143], v[126:127], v[182:183]
	v_pk_fma_f32 v[194:195], v[144:145], v[16:17], v[194:195]
	v_pk_fma_f32 v[196:197], v[144:145], v[32:33], v[196:197]
	v_pk_fma_f32 v[198:199], v[144:145], v[48:49], v[198:199]
	v_pk_fma_f32 v[200:201], v[144:145], v[64:65], v[200:201]
	v_pk_fma_f32 v[202:203], v[144:145], v[80:81], v[202:203]
	v_pk_fma_f32 v[204:205], v[144:145], v[96:97], v[204:205]
	v_pk_fma_f32 v[206:207], v[144:145], v[112:113], v[206:207]
	v_pk_fma_f32 v[182:183], v[144:145], v[128:129], v[182:183]
	v_add_f32_e32 v194, v194, v195
	v_add_f32_e32 v196, v196, v197
	v_add_f32_e32 v198, v198, v199
	v_add_f32_e32 v200, v200, v201
	v_add_f32_e32 v202, v202, v203
	v_add_f32_e32 v204, v204, v205
	v_add_f32_e32 v206, v206, v207
	v_add_f32_e32 v182, v182, v183
	s_nop 1
	v_permlane32_swap_b32_e32 v194, v202
	v_permlane32_swap_b32_e32 v196, v204
	v_permlane32_swap_b32_e32 v198, v206
	v_permlane32_swap_b32_e32 v200, v182
	v_add_f32_e32 v194, v194, v202
	v_add_f32_e32 v196, v196, v204
	v_add_f32_e32 v198, v198, v206
	v_add_f32_e32 v200, v200, v182
	s_nop 1
	v_permlane16_swap_b32_e32 v194, v198
	v_permlane16_swap_b32_e32 v196, v200
	v_add_f32_e32 v194, v194, v198
	v_add_f32_e32 v196, v196, v200
	s_nop 1
	v_add_f32_dpp v240, v194, v194 row_ror:8 row_mask:0xf bank_mask:0x3
	v_add_f32_dpp v240, v196, v196 row_ror:8 row_mask:0xf bank_mask:0xc
	s_nop 1
	v_add_f32_dpp v241, v233, v233 row_half_mirror row_mask:0xf bank_mask:0x5
	v_add_f32_dpp v241, v237, v237 row_half_mirror row_mask:0xf bank_mask:0xa
	v_add_f32_dpp v242, v234, v234 row_half_mirror row_mask:0xf bank_mask:0x5
	v_add_f32_dpp v242, v238, v238 row_half_mirror row_mask:0xf bank_mask:0xa
	v_add_f32_dpp v243, v235, v235 row_half_mirror row_mask:0xf bank_mask:0x5
	v_add_f32_dpp v243, v239, v239 row_half_mirror row_mask:0xf bank_mask:0xa
	v_add_f32_dpp v244, v236, v236 row_half_mirror row_mask:0xf bank_mask:0x5
; __device__ __forceinline__ float reduce8(const float (&d)[8], int lane) {
;     ...
;     for (int i = 0; i < 2; ++i) { const float snd = h16 ? e[i] : e[2 + i], kp = h16 ? e[2 + i] : e[i]; f[i] = kp + __shfl_xor(snd, 16); }
;     const float snd = h8 ? f[0] : f[1], kp = h8 ? f[1] : f[0];
;     float g = kp + __shfl_xor(snd, 8);
;     g += __shfl_xor(g, 4); g += __shfl_xor(g, 2); g += __shfl_xor(g, 1);
;     return g;
; __device__ __forceinline__ void fg_tail(const Args& a, int l, LAS unsigned char* lds, const int tid) {
;     ...
;     for (int chunk = blockIdx.x * 8 + wid; chunk * 8 < MT; chunk += gridDim.x * 8) {
;         const int rowc = chunk * 8, b = rowc >> 11;
;         f32x4 sh[4];
; #pragma unroll
;         for (int q = 0; q < 4; ++q) sh[q] = *(const f32x4*)(mod + (size_t)b * MODW + 16 * lane + 4 * q);
; #pragma unroll 1
;         for (int jb = 0; jb < 8; jb += 4) {
;             f32x4 rs4v[4]; u32x4 w0v[4], w1v[4];
; #pragma unroll
;             for (int j = 0; j < 4; ++j) { const int row = rowc + jb + j; rs4v[j] = *(const f32x4*)(rowss + (size_t)row * 4); w0v[j] = *(const u32x4*)(H + (size_t)row * DM + 16 * lane); w1v[j] = *(const u32x4*)(H + (size_t)row * DM + 16 * lane + 8); }
; #pragma unroll
;             for (int j = 0; j < 4; ++j) {
;                 const int row = rowc + jb + j;
;                 const f32x4 rs4 = rs4v[j]; const u32x4 w0 = w0v[j], w1 = w1v[j];
;                 const float r = 1.0f / sqrtf(((rs4[0] + rs4[1]) + (rs4[2] + rs4[3])) * (1.0f / 1024.0f) + EPS);
;                 float h[16];
; #pragma unroll
;                 for (int i = 0; i < 4; ++i) { h[2 * i] = __uint_as_float(w0[i] << 16); h[2 * i + 1] = __uint_as_float(w0[i] & 0xffff0000u); h[8 + 2 * i] = __uint_as_float(w1[i] << 16); h[8 + 2 * i + 1] = __uint_as_float(w1[i] & 0xffff0000u); }
; #pragma unroll
;                 for (int q = 0; q < 4; ++q) { h[4 * q] = h[4 * q] * r + sh[q][0]; h[4 * q + 1] = h[4 * q + 1] * r + sh[q][1]; h[4 * q + 2] = h[4 * q + 2] * r + sh[q][2]; h[4 * q + 3] = h[4 * q + 3] * r + sh[q][3]; }
;                 float d8[8];
; #pragma unroll
;                 for (int j8 = 0; j8 < 8; ++j8) { float acc = 0.f;
; #pragma unroll
;                     for (int q = 0; q < 4; ++q) { const f32x4 w = wl[(j8 * 4 + q) * 64 + lane]; acc += (h[4 * q] * w[0] + h[4 * q + 1] * w[1]) + (h[4 * q + 2] * w[2] + h[4 * q + 3] * w[3]); }
;                     d8[j8] = acc; }
	v_add_f32_dpp v244, v240, v240 row_half_mirror row_mask:0xf bank_mask:0xa
	v_cndmask_b32_e64 v235, v243, v241, s[30:31]
	v_cndmask_b32_e64 v237, v241, v243, s[30:31]
	v_cndmask_b32_e64 v236, v244, v242, s[30:31]
	v_cndmask_b32_e64 v238, v242, v244, s[30:31]
	s_nop 1
	v_add_f32_dpp v233, v235, v237 quad_perm:[2,3,0,1] row_mask:0xf bank_mask:0xf
	v_add_f32_dpp v234, v236, v238 quad_perm:[2,3,0,1] row_mask:0xf bank_mask:0xf
	v_cndmask_b32_e64 v239, v234, v233, s[40:41]
	v_cndmask_b32_e64 v240, v233, v234, s[40:41]
	s_nop 1
	v_add_f32_dpp v245, v239, v240 quad_perm:[1,0,3,2] row_mask:0xf bank_mask:0xf
	v_fma_f32 v182, v247, v245, v248
	v_mul_f32_e64 v183, |v182|, s26
	v_exp_f32_e32 v183, v183
	v_min_f32_e32 v182, 0, v182
	v_add_f32_e32 v184, 1.0, v183
	v_add_f32_e32 v185, -1.0, v184
	v_sub_f32_e32 v216, v185, v184
	v_sub_f32_e32 v185, v183, v185
	v_add_f32_e32 v216, 1.0, v216
	v_frexp_mant_f32_e32 v187, v184
	v_add_f32_e32 v185, v185, v216
	v_cvt_f64_f32_e32 v[216:217], v184
	v_frexp_exp_i32_f64_e32 v216, v[216:217]
	v_cmp_gt_f32_e32 vcc, s17, v187
	s_nop 1
	v_subbrev_co_u32_e32 v218, vcc, 0, v216, vcc
	v_sub_u32_e32 v187, 0, v218
	v_ldexp_f32 v184, v184, v187
	v_ldexp_f32 v185, v185, v187
	v_add_f32_e32 v187, -1.0, v184
	v_add_f32_e32 v217, 1.0, v184
	v_add_f32_e32 v216, 1.0, v187
	v_add_f32_e32 v228, -1.0, v217
	v_sub_f32_e32 v216, v184, v216
	v_sub_f32_e32 v184, v184, v228
	v_add_f32_e32 v184, v185, v184
	v_add_f32_e32 v216, v185, v216
	v_add_f32_e32 v185, v217, v184
	v_rcp_f32_e32 v228, v185
	v_sub_f32_e32 v217, v185, v217
	v_sub_f32_e32 v184, v184, v217
	v_add_f32_e32 v217, v187, v216
	v_mul_f32_e32 v233, v217, v228
	v_mul_f32_e32 v234, v185, v233
	v_fma_f32 v236, v233, v185, -v234
	v_sub_f32_e32 v187, v217, v187
	v_fmac_f32_e32 v236, v233, v184
	v_sub_f32_e32 v187, v216, v187
	v_add_f32_e32 v216, v234, v236
	v_sub_f32_e32 v235, v217, v216
	v_pk_add_f32 v[238:239], v[216:217], v[234:235] neg_lo:[0,1] neg_hi:[0,1]
	v_mov_b32_e32 v237, v216
	v_pk_add_f32 v[216:217], v[238:239], v[236:237] neg_lo:[0,1] neg_hi:[0,1]
	v_cmp_neq_f32_e32 vcc, s43, v183
	v_add_f32_e32 v187, v187, v217
	v_add_f32_e32 v187, v216, v187
	v_add_f32_e32 v217, v235, v187
	v_mul_f32_e32 v240, v228, v217
	v_mul_f32_e32 v234, v185, v240
	v_fma_f32 v236, v240, v185, -v234
	v_fmac_f32_e32 v236, v240, v184
	v_add_f32_e32 v216, v234, v236
	v_sub_f32_e32 v184, v235, v217
	v_sub_f32_e32 v235, v217, v216
	v_pk_add_f32 v[238:239], v[216:217], v[234:235] neg_lo:[0,1] neg_hi:[0,1]
	v_mov_b32_e32 v237, v216
	v_add_f32_e32 v184, v187, v184
	v_pk_add_f32 v[216:217], v[238:239], v[236:237] neg_lo:[0,1] neg_hi:[0,1]
	v_add_f32_e32 v185, v233, v240
	v_add_f32_e32 v184, v184, v217
	v_add_f32_e32 v184, v216, v184
	v_add_f32_e32 v184, v235, v184
	v_sub_f32_e32 v187, v185, v233
	v_mul_f32_e32 v184, v228, v184
	v_sub_f32_e32 v187, v240, v187
	v_add_f32_e32 v184, v187, v184
	v_add_f32_e32 v217, v185, v184
	v_cvt_f32_i32_e32 v216, v218
	v_mul_f32_e32 v228, v217, v217
	v_fmamk_f32 v187, v228, 0x3e9b6dac, v227
	v_fmaak_f32 v187, v228, v187, 0x3f2aaada
	v_sub_f32_e32 v185, v217, v185
	v_ldexp_f32 v235, v217, 1
	v_mul_f32_e32 v217, v217, v228
	v_pk_mul_f32 v[236:237], v[216:217], v[186:187]
	v_sub_f32_e32 v184, v184, v185
	v_fma_f32 v234, v216, s18, -v236
	v_fmac_f32_e32 v234, 0xb102e308, v216
	v_pk_add_f32 v[216:217], v[236:237], v[234:235]
	v_ldexp_f32 v184, v184, 1
	v_sub_f32_e32 v185, v217, v235
	v_sub_f32_e32 v185, v237, v185
	v_add_f32_e32 v239, v184, v185
	v_mov_b32_e32 v238, v236
	v_pk_add_f32 v[236:237], v[216:217], v[236:237] neg_lo:[0,1] neg_hi:[0,1]
	v_pk_add_f32 v[240:241], v[216:217], v[238:239]
	v_mov_b32_e32 v235, v216
	v_mov_b32_e32 v237, v241
	v_pk_add_f32 v[242:243], v[234:235], v[236:237] neg_lo:[0,1] neg_hi:[0,1]
	v_pk_add_f32 v[234:235], v[234:235], v[236:237]
	v_mov_b32_e32 v238, v239
	v_pk_add_f32 v[236:237], v[234:235], v[216:217] op_sel:[1,0] op_sel_hi:[0,1] neg_lo:[0,1] neg_hi:[0,1]
	v_pk_add_f32 v[244:245], v[240:241], v[236:237] op_sel_hi:[1,0] neg_lo:[0,1] neg_hi:[0,1]
	v_mov_b32_e32 v240, v241
	v_mov_b32_e32 v241, v235
	v_pk_mov_b32 v[236:237], v[216:217], v[236:237] op_sel:[1,0]
	v_mov_b32_e32 v239, v216
	v_pk_add_f32 v[236:237], v[240:241], v[236:237] neg_lo:[0,1] neg_hi:[0,1]
	v_mov_b32_e32 v244, v242
	v_pk_add_f32 v[216:217], v[238:239], v[236:237] neg_lo:[0,1] neg_hi:[0,1]
	v_mov_b32_e32 v243, v235
	v_pk_add_f32 v[236:237], v[244:245], v[216:217]
	s_nop 0
	v_pk_add_f32 v[238:239], v[236:237], v[236:237] op_sel:[0,1] op_sel_hi:[1,0]
	s_nop 0
	v_pk_add_f32 v[234:235], v[234:235], v[238:239] op_sel:[1,0] op_sel_hi:[0,1]
	v_mov_b32_e32 v237, v234
	v_pk_add_f32 v[240:241], v[236:237], v[242:243] neg_lo:[0,1] neg_hi:[0,1]
	v_mov_b32_e32 v217, v238
	v_sub_f32_e32 v184, v236, v240
	v_pk_add_f32 v[216:217], v[216:217], v[240:241] neg_lo:[0,1] neg_hi:[0,1]
	v_sub_f32_e32 v184, v242, v184
	v_add_f32_e32 v184, v216, v184
	v_add_f32_e32 v184, v184, v217
	v_add_f32_e32 v184, v234, v184
	v_cndmask_b32_e32 v184, v229, v184, vcc
	v_cmp_ngt_f32_e32 vcc, -1.0, v183
	s_nop 1
	v_cndmask_b32_e32 v184, v231, v184, vcc
	v_cmp_neq_f32_e32 vcc, -1.0, v183
	s_nop 1
	v_cndmask_b32_e32 v184, v232, v184, vcc
	v_cmp_lt_f32_e64 vcc, |v183|, s19
	s_nop 1
	v_cndmask_b32_e32 v183, v184, v183, vcc
	v_sub_f32_e32 v182, v182, v183
	global_store_dword v246, v182, s[4:5]
	v_add_u32_e32 v0, s92, v0
	s_nop 0
	v_readfirstlane_b32 s52, v0
	s_cmp_le_i32 s52, s83
	s_cbranch_scc0 .Lfg_exit
	v_lshlrev_b32_e32 v184, 14, v0
	v_lshl_add_u32 v184, v208, 5, v184
	v_lshrrev_b32_e32 v215, 8, v0
	v_mul_u32_u24_e32 v215, 0x6000, v215
	v_lshl_add_u32 v215, v208, 6, v215
	v_and_b32_e32 v216, 7, v208
	v_lshlrev_b32_e32 v217, 7, v0
	v_lshl_add_u32 v217, v216, 4, v217
	v_lshlrev_b32_e32 v246, 8, v0
	v_lshl_add_u32 v246, v216, 5, v246
	v_lshrrev_b32_e32 v216, 3, v208
	v_lshl_add_u32 v246, v216, 2, v246
	global_load_dwordx4 v[130:133], v215, s[2:3]
	global_load_dwordx4 v[134:137], v215, s[2:3] offset:16
	global_load_dwordx4 v[138:141], v215, s[2:3] offset:32
	global_load_dwordx4 v[142:145], v215, s[2:3] offset:48
	global_load_dwordx4 v[178:181], v217, s[34:35]
	global_load_dwordx4 v[146:149], v184, s[94:95]
	global_load_dwordx4 v[150:153], v184, s[94:95] offset:16
	global_load_dwordx4 v[154:157], v184, s[94:95] offset:2048
	global_load_dwordx4 v[158:161], v184, s[94:95] offset:2064
	v_add_u32_e32 v184, 0x1000, v184
	global_load_dwordx4 v[162:165], v184, s[94:95]
	global_load_dwordx4 v[166:169], v184, s[94:95] offset:16
	global_load_dwordx4 v[170:173], v184, s[94:95] offset:2048
	global_load_dwordx4 v[174:177], v184, s[94:95] offset:2064
	v_add_u32_e32 v184, 0x1000, v184
	s_branch .Lfg_loop
